# FFT pass loops: LDS addresses strength-reduced to one base register plus immediate offsets, dead integer VALU removed
# speedup vs baseline: 1.0179x; 1.0023x over previous
;     static __device__ __forceinline__ float sl(float g, float up) { return g * __builtin_amdgcn_rcpf(1.0f + __builtin_amdgcn_exp2f(-1.4426950408889634f * g)) * up; }
; #define tid ltid()
; template <int LR, bool INV>
; __device__ __forceinline__ void fft_pass(float2* X, const int N, const int sl, const int tid) {
;     ...
;   for (int g = tid; g < (N >> LR); g += NTHR) {
;     const int r = g & (s - 1);
;     const int i0 = ((g >> sl) << (sl + LR)) + r;
;     float2 x[R];
; #pragma unroll
;     for (int m = 0; m < R; ++m) x[m] = X[PIDX(i0 + (m << sl))];
.LBB0_651:
	v_and_or_b32 v31, v30, s67, v28
	v_ashrrev_i32_e32 v32, 4, v31
	v_lshlrev_b32_e32 v32, 3, v32
	v_lshlrev_b32_e32 v33, 3, v31
	v_add3_u32 v50, s52, v32, v33


;     static __device__ __forceinline__ float sl(float g, float up) { return g * __builtin_amdgcn_rcpf(1.0f + __builtin_amdgcn_exp2f(-1.4426950408889634f * g)) * up; }
; #define tid ltid()
; template <int LR, bool INV>
; __device__ __forceinline__ void fft_pass(float2* X, const int N, const int sl, const int tid) {
;     ...
;   for (int g = tid; g < (N >> LR); g += NTHR) {
;     const int r = g & (s - 1);
;     const int i0 = ((g >> sl) << (sl + LR)) + r;
;     float2 x[R];
; #pragma unroll
;     for (int m = 0; m < R; ++m) x[m] = X[PIDX(i0 + (m << sl))];
	v_or_b32_e32 v31, 0xe00, v31

;     static __device__ __forceinline__ float sl(float g, float up) { return g * __builtin_amdgcn_rcpf(1.0f + __builtin_amdgcn_exp2f(-1.4426950408889634f * g)) * up; }
; #define tid ltid()
; template <int LR, bool INV>
; __device__ __forceinline__ void fft_pass(float2* X, const int N, const int sl, const int tid) {
;     ...
;   for (int g = tid; g < (N >> LR); g += NTHR) {
;     const int r = g & (s - 1);
;     const int i0 = ((g >> sl) << (sl + LR)) + r;
;     float2 x[R];
; #pragma unroll
;     for (int m = 0; m < R; ++m) x[m] = X[PIDX(i0 + (m << sl))];
	v_ashrrev_i32_e32 v31, 4, v31

;     static __device__ __forceinline__ float sl(float g, float up) { return g * __builtin_amdgcn_rcpf(1.0f + __builtin_amdgcn_exp2f(-1.4426950408889634f * g)) * up; }
; #define tid ltid()
; template <int LR, bool INV>
; __device__ __forceinline__ void fft_pass(float2* X, const int N, const int sl, const int tid) {
;     ...
;   for (int g = tid; g < (N >> LR); g += NTHR) {
;     const int r = g & (s - 1);
;     const int i0 = ((g >> sl) << (sl + LR)) + r;
;     float2 x[R];
; #pragma unroll
;     for (int m = 0; m < R; ++m) x[m] = X[PIDX(i0 + (m << sl))];
	v_lshlrev_b32_e32 v31, 3, v31

;     static __device__ __forceinline__ float sl(float g, float up) { return g * __builtin_amdgcn_rcpf(1.0f + __builtin_amdgcn_exp2f(-1.4426950408889634f * g)) * up; }
; __device__ __forceinline__ float2 cmul(float2 a, float2 b) { return make_float2(a.x * b.x - a.y * b.y, a.x * b.y + a.y * b.x); }
; #define tid ltid()
; template <int LR, bool INV>
; __device__ __forceinline__ void fft_stages(float2 (&x)[1 << LR], const int r, const int s) {
;   constexpr int R = 1 << LR;
; #pragma unroll
;   for (int st = 0; st < LR; ++st) {
;     const int hl = INV ? (1 << st) : (R >> (st + 1));
;     const float fb = (float)r * (0.5f / (float)(hl * s));
;     const float2 wb = make_float2(__builtin_amdgcn_cosf(fb), INV ? __builtin_amdgcn_sinf(fb) : -__builtin_amdgcn_sinf(fb));
; #pragma unroll
;     for (int m = 0; m < R; ++m) {
;       if (m & hl) continue;
;       const int k = m & (hl - 1); const int j = k * (8 / hl);
;       const float2 wc = make_float2(c16(j), INV ? s16(j) : -s16(j));
;       const float2 tw = cmul(wb, wc);
;       if (!INV) { const float2 p = x[m], q = x[m + hl]; x[m] = make_float2(p.x + q.x, p.y + q.y); x[m + hl] = cmul(make_float2(p.x - q.x, p.y - q.y), tw); }
;       else { const float2 p = x[m], q = cmul(x[m + hl], tw); x[m] = make_float2(p.x + q.x, p.y + q.y); x[m + hl] = make_float2(p.x - q.x, p.y - q.y); }
;     }
;   }
; }
; template <int LR, bool INV>
; __device__ __forceinline__ void fft_pass(float2* X, const int N, const int sl, const int tid) {
;   constexpr int R = 1 << LR;
;   const int s = 1 << sl;
;   for (int g = tid; g < (N >> LR); g += NTHR) {
;     const int r = g & (s - 1);
;     const int i0 = ((g >> sl) << (sl + LR)) + r;
;     float2 x[R];
; #pragma unroll
;     for (int m = 0; m < R; ++m) x[m] = X[PIDX(i0 + (m << sl))];
;     fft_stages<LR, INV>(x, r, s);
; #pragma unroll
;     for (int m = 0; m < R; ++m) X[PIDX(i0 + (m << sl))] = x[m];
;   }
	v_add3_u32 v31, s52, v31, v33
	ds_read_b64 v[32:33], v50
	ds_read_b64 v[34:35], v50 offset:4352
	ds_read_b64 v[36:37], v50 offset:8704
	ds_read_b64 v[38:39], v50 offset:13056
	ds_read_b64 v[40:41], v50 offset:17408
	ds_read_b64 v[42:43], v50 offset:21760
	ds_read_b64 v[44:45], v50 offset:26112
	ds_read_b64 v[46:47], v50 offset:30464
	v_add_u32_e32 v29, 0x200, v29
	s_waitcnt lgkmcnt(3)
	v_add_f32_e32 v48, v32, v40
	v_add_f32_e32 v49, v33, v41
	v_sub_f32_e32 v32, v32, v40
	v_sub_f32_e32 v33, v33, v41
	s_waitcnt lgkmcnt(2)
	v_add_f32_e32 v40, v34, v42
	v_add_f32_e32 v41, v35, v43
	v_sub_f32_e32 v34, v34, v42
	v_sub_f32_e32 v35, v35, v43
	s_waitcnt lgkmcnt(1)
	v_add_f32_e32 v42, v36, v44
	v_add_f32_e32 v43, v37, v45
	v_sub_f32_e32 v36, v36, v44
	v_sub_f32_e32 v37, v37, v45
	s_waitcnt lgkmcnt(0)
	v_add_f32_e32 v44, v38, v46
	v_add_f32_e32 v45, v39, v47
	v_sub_f32_e32 v38, v38, v46
	v_sub_f32_e32 v39, v39, v47
	v_add_f32_e32 v46, v48, v42
	v_add_f32_e32 v47, v49, v43
	v_sub_f32_e32 v42, v48, v42
	v_sub_f32_e32 v43, v49, v43
	v_add_f32_e32 v48, v40, v44
	v_add_f32_e32 v49, v41, v45
	v_sub_f32_e32 v40, v40, v44
	v_sub_f32_e32 v41, v41, v45
	v_add_f32_e32 v44, v46, v48
	v_add_f32_e32 v45, v47, v49
	v_sub_f32_e32 v46, v46, v48
	v_sub_f32_e32 v47, v47, v49
	ds_write_b64 v50, v[44:45]
	v_mul_f32_e32 v44, v14, v47
	v_mul_f32_e32 v45, v15, v47
	v_cmp_lt_i32_e32 vcc, -1, v29
	v_fma_f32 v48, v12, v46, -v44
	v_fma_f32 v45, v13, v46, v45
	v_add_u32_e32 v30, 0x1000, v30
	v_mov_b32_e32 v49, v45
	v_mul_f32_e32 v44, v16, v43
	v_mul_f32_e32 v45, v17, v43
	ds_write_b64 v50, v[48:49] offset:4352
	v_fma_f32 v46, v8, v42, -v44
	v_fma_f32 v43, v9, v42, v45
	s_or_b64 s[14:15], vcc, s[14:15]
	v_mov_b32_e32 v47, v43
	v_mul_f32_e32 v42, v18, v41
	v_mul_f32_e32 v43, v19, v41
	v_fma_f32 v44, v10, v40, -v42
	v_fma_f32 v41, v11, v40, v43
	v_mov_b32_e32 v45, v41
	v_add_f32_e32 v40, v46, v44
	v_add_f32_e32 v41, v47, v45
	v_sub_f32_e32 v42, v46, v44
	v_sub_f32_e32 v43, v47, v45
	ds_write_b64 v50, v[40:41] offset:8704
	v_mul_f32_e32 v40, v14, v43
	v_mul_f32_e32 v41, v15, v43
	v_fma_f32 v44, v12, v42, -v40
	v_fma_f32 v41, v13, v42, v41
	v_mov_b32_e32 v45, v41
	v_mul_f32_e32 v40, v20, v33
	v_mul_f32_e32 v41, v21, v33
	ds_write_b64 v50, v[44:45] offset:13056
	v_fma_f32 v42, v0, v32, -v40
	v_fma_f32 v33, v1, v32, v41
	v_mov_b32_e32 v43, v33
	v_mul_f32_e32 v32, v22, v35
	v_mul_f32_e32 v33, v23, v35
	v_fma_f32 v40, v2, v34, -v32
	v_fma_f32 v33, v3, v34, v33
	v_mov_b32_e32 v41, v33
	v_mul_f32_e32 v32, v24, v37
	v_mul_f32_e32 v33, v25, v37
	v_fma_f32 v34, v4, v36, -v32
	v_fma_f32 v33, v5, v36, v33
	v_mov_b32_e32 v35, v33
	v_mul_f32_e32 v32, v26, v39
	v_mul_f32_e32 v33, v27, v39
	v_fma_f32 v36, v6, v38, -v32
	v_fma_f32 v33, v7, v38, v33
	v_mov_b32_e32 v37, v33
	v_add_f32_e32 v32, v42, v34
	v_add_f32_e32 v33, v43, v35
	v_add_f32_e32 v38, v40, v36
	v_add_f32_e32 v39, v41, v37
	v_sub_f32_e32 v36, v40, v36
	v_sub_f32_e32 v37, v41, v37
	v_add_f32_e32 v40, v32, v38
	v_add_f32_e32 v41, v33, v39
	v_sub_f32_e32 v32, v32, v38
	v_sub_f32_e32 v33, v33, v39
	v_sub_f32_e32 v34, v42, v34
	v_sub_f32_e32 v35, v43, v35
	v_mul_f32_e32 v38, v14, v33
	v_mul_f32_e32 v39, v15, v33
	ds_write_b64 v50, v[40:41] offset:17408
	v_fma_f32 v40, v12, v32, -v38
	v_fma_f32 v33, v13, v32, v39
	v_mov_b32_e32 v41, v33
	v_mul_f32_e32 v32, v16, v35
	v_mul_f32_e32 v33, v17, v35
	ds_write_b64 v50, v[40:41] offset:21760
	v_fma_f32 v38, v8, v34, -v32
	v_fma_f32 v33, v9, v34, v33
	v_mov_b32_e32 v39, v33
	v_mul_f32_e32 v32, v18, v37
	v_mul_f32_e32 v33, v19, v37
	v_fma_f32 v34, v10, v36, -v32
	v_fma_f32 v33, v11, v36, v33
	v_mov_b32_e32 v35, v33
	v_add_f32_e32 v32, v38, v34
	v_add_f32_e32 v33, v39, v35
	v_sub_f32_e32 v34, v38, v34
	v_sub_f32_e32 v35, v39, v35
	ds_write_b64 v50, v[32:33] offset:26112
	v_mul_f32_e32 v32, v14, v35
	v_mul_f32_e32 v33, v15, v35
	v_fma_f32 v36, v12, v34, -v32
	v_fma_f32 v32, v12, v34, v32
	v_fma_f32 v33, v13, v34, v33
	v_mov_b32_e32 v37, v33
	ds_write_b64 v50, v[36:37] offset:30464
	s_andn2_b64 exec, exec, s[14:15]
	s_cbranch_execnz .LBB0_651

;     static __device__ __forceinline__ float sl(float g, float up) { return g * __builtin_amdgcn_rcpf(1.0f + __builtin_amdgcn_exp2f(-1.4426950408889634f * g)) * up; }
; #define tid ltid()
; template <int LR, bool INV>
; __device__ __forceinline__ void fft_pass(float2* X, const int N, const int sl, const int tid) {
;     ...
;   for (int g = tid; g < (N >> LR); g += NTHR) {
;     const int r = g & (s - 1);
;     const int i0 = ((g >> sl) << (sl + LR)) + r;
;     float2 x[R];
; #pragma unroll
;     for (int m = 0; m < R; ++m) x[m] = X[PIDX(i0 + (m << sl))];
.LBB0_656:
	v_and_or_b32 v64, v63, s2, v61
	v_ashrrev_i32_e32 v65, 4, v64
	v_lshlrev_b32_e32 v66, 3, v64
	v_lshlrev_b32_e32 v65, 3, v65
	v_add3_u32 v98, s52, v66, v65


;     static __device__ __forceinline__ float sl(float g, float up) { return g * __builtin_amdgcn_rcpf(1.0f + __builtin_amdgcn_exp2f(-1.4426950408889634f * g)) * up; }
; __device__ __forceinline__ float2 cmul(float2 a, float2 b) { return make_float2(a.x * b.x - a.y * b.y, a.x * b.y + a.y * b.x); }
; #define tid ltid()
; template <int LR, bool INV>
; __device__ __forceinline__ void fft_stages(float2 (&x)[1 << LR], const int r, const int s) {
;   constexpr int R = 1 << LR;
; #pragma unroll
;   for (int st = 0; st < LR; ++st) {
;     const int hl = INV ? (1 << st) : (R >> (st + 1));
;     const float fb = (float)r * (0.5f / (float)(hl * s));
;     const float2 wb = make_float2(__builtin_amdgcn_cosf(fb), INV ? __builtin_amdgcn_sinf(fb) : -__builtin_amdgcn_sinf(fb));
; #pragma unroll
;     for (int m = 0; m < R; ++m) {
;       if (m & hl) continue;
;       const int k = m & (hl - 1); const int j = k * (8 / hl);
;       const float2 wc = make_float2(c16(j), INV ? s16(j) : -s16(j));
;       const float2 tw = cmul(wb, wc);
;       if (!INV) { const float2 p = x[m], q = x[m + hl]; x[m] = make_float2(p.x + q.x, p.y + q.y); x[m + hl] = cmul(make_float2(p.x - q.x, p.y - q.y), tw); }
;       else { const float2 p = x[m], q = cmul(x[m + hl], tw); x[m] = make_float2(p.x + q.x, p.y + q.y); x[m + hl] = make_float2(p.x - q.x, p.y - q.y); }
;     }
;   }
; }
; template <int LR, bool INV>
; __device__ __forceinline__ void fft_pass(float2* X, const int N, const int sl, const int tid) {
;   constexpr int R = 1 << LR;
;   const int s = 1 << sl;
;   for (int g = tid; g < (N >> LR); g += NTHR) {
;     const int r = g & (s - 1);
;     const int i0 = ((g >> sl) << (sl + LR)) + r;
;     float2 x[R];
; #pragma unroll
;     for (int m = 0; m < R; ++m) x[m] = X[PIDX(i0 + (m << sl))];
;     fft_stages<LR, INV>(x, r, s);
; #pragma unroll
;     for (int m = 0; m < R; ++m) X[PIDX(i0 + (m << sl))] = x[m];
;   }
	ds_read_b64 v[64:65], v98
	ds_read_b64 v[66:67], v98 offset:4352
	ds_read_b64 v[68:69], v98 offset:8704
	ds_read_b64 v[70:71], v98 offset:13056
	ds_read_b64 v[72:73], v98 offset:17408
	ds_read_b64 v[74:75], v98 offset:21760
	ds_read_b64 v[76:77], v98 offset:26112
	ds_read_b64 v[78:79], v98 offset:30464
	ds_read_b64 v[80:81], v98 offset:34816
	ds_read_b64 v[82:83], v98 offset:39168
	ds_read_b64 v[84:85], v98 offset:43520
	ds_read_b64 v[86:87], v98 offset:47872
	ds_read_b64 v[88:89], v98 offset:52224
	ds_read_b64 v[90:91], v98 offset:56576
	ds_read_b64 v[92:93], v98 offset:60928
	ds_read_b64 v[94:95], v98 offset:65280
	s_waitcnt lgkmcnt(7)
	v_add_f32_e32 v96, v64, v80
	v_add_f32_e32 v97, v65, v81
	v_sub_f32_e32 v64, v64, v80
	v_sub_f32_e32 v65, v65, v81
	s_waitcnt lgkmcnt(6)
	v_add_f32_e32 v80, v66, v82
	v_add_f32_e32 v81, v67, v83
	v_sub_f32_e32 v66, v66, v82
	v_sub_f32_e32 v67, v67, v83
	s_waitcnt lgkmcnt(5)
	v_add_f32_e32 v82, v68, v84
	v_add_f32_e32 v83, v69, v85
	v_sub_f32_e32 v68, v68, v84
	v_sub_f32_e32 v69, v69, v85
	s_waitcnt lgkmcnt(4)
	v_add_f32_e32 v84, v70, v86
	v_add_f32_e32 v85, v71, v87
	v_sub_f32_e32 v70, v70, v86
	v_sub_f32_e32 v71, v71, v87
	s_waitcnt lgkmcnt(3)
	v_add_f32_e32 v86, v72, v88
	v_add_f32_e32 v87, v73, v89
	v_sub_f32_e32 v72, v72, v88
	v_sub_f32_e32 v73, v73, v89
	s_waitcnt lgkmcnt(2)
	v_add_f32_e32 v88, v74, v90
	v_add_f32_e32 v89, v75, v91
	v_sub_f32_e32 v74, v74, v90
	v_sub_f32_e32 v75, v75, v91
	s_waitcnt lgkmcnt(1)
	v_add_f32_e32 v90, v76, v92
	v_add_f32_e32 v91, v77, v93
	v_sub_f32_e32 v76, v76, v92
	v_sub_f32_e32 v77, v77, v93
	s_waitcnt lgkmcnt(0)
	v_add_f32_e32 v92, v78, v94
	v_add_f32_e32 v93, v79, v95
	v_sub_f32_e32 v78, v78, v94
	v_sub_f32_e32 v79, v79, v95
	v_add_f32_e32 v94, v96, v86
	v_add_f32_e32 v95, v97, v87
	v_sub_f32_e32 v86, v96, v86
	v_sub_f32_e32 v87, v97, v87
	v_add_f32_e32 v96, v80, v88
	v_add_f32_e32 v97, v81, v89
	v_sub_f32_e32 v80, v80, v88
	v_sub_f32_e32 v81, v81, v89
	v_add_f32_e32 v88, v82, v90
	v_add_f32_e32 v89, v83, v91
	v_sub_f32_e32 v82, v82, v90
	v_sub_f32_e32 v83, v83, v91
	v_add_f32_e32 v90, v84, v92
	v_add_f32_e32 v91, v85, v93
	v_sub_f32_e32 v84, v84, v92
	v_sub_f32_e32 v85, v85, v93
	v_add_f32_e32 v92, v94, v88
	v_add_f32_e32 v93, v95, v89
	v_sub_f32_e32 v88, v94, v88
	v_sub_f32_e32 v89, v95, v89
	v_add_f32_e32 v94, v96, v90
	v_add_f32_e32 v95, v97, v91
	v_sub_f32_e32 v90, v96, v90
	v_sub_f32_e32 v91, v97, v91
	v_add_f32_e32 v96, v92, v94
	v_add_f32_e32 v97, v93, v95
	v_sub_f32_e32 v92, v92, v94
	v_sub_f32_e32 v93, v93, v95
	ds_write_b64 v98, v[96:97]
	v_mul_f32_e32 v94, v30, v93
	v_mul_f32_e32 v95, v31, v93
	v_add_u32_e32 v62, 0x200, v62
	v_fma_f32 v96, v28, v92, -v94
	v_fma_f32 v93, v29, v92, v95
	v_cmp_lt_i32_e32 vcc, -1, v62
	v_mov_b32_e32 v97, v93
	v_mul_f32_e32 v92, v32, v89
	v_mul_f32_e32 v93, v33, v89
	ds_write_b64 v98, v[96:97] offset:4352
	v_fma_f32 v94, v24, v88, -v92
	v_fma_f32 v89, v25, v88, v93
	v_add_u32_e32 v63, 0x2000, v63
	v_mov_b32_e32 v95, v89
	v_mul_f32_e32 v88, v34, v91
	v_mul_f32_e32 v89, v35, v91
	s_or_b64 s[14:15], vcc, s[14:15]
	v_fma_f32 v92, v26, v90, -v88
	v_fma_f32 v89, v27, v90, v89
	v_mov_b32_e32 v93, v89
	v_add_f32_e32 v88, v94, v92
	v_add_f32_e32 v89, v95, v93
	v_sub_f32_e32 v90, v94, v92
	v_sub_f32_e32 v91, v95, v93
	ds_write_b64 v98, v[88:89] offset:8704
	v_mul_f32_e32 v88, v30, v91
	v_mul_f32_e32 v89, v31, v91
	v_fma_f32 v92, v28, v90, -v88
	v_fma_f32 v89, v29, v90, v89
	v_mov_b32_e32 v93, v89
	v_mul_f32_e32 v88, v36, v87
	v_mul_f32_e32 v89, v37, v87
	ds_write_b64 v98, v[92:93] offset:13056
	v_fma_f32 v90, v16, v86, -v88
	v_fma_f32 v87, v17, v86, v89
	v_mov_b32_e32 v91, v87
	v_mul_f32_e32 v86, v38, v81
	v_mul_f32_e32 v87, v39, v81
	v_fma_f32 v88, v18, v80, -v86
	v_fma_f32 v81, v19, v80, v87
	v_mov_b32_e32 v89, v81
	v_mul_f32_e32 v80, v40, v83
	v_mul_f32_e32 v81, v41, v83
	v_fma_f32 v86, v20, v82, -v80
	v_fma_f32 v81, v21, v82, v81
	v_mov_b32_e32 v87, v81
	v_mul_f32_e32 v80, v42, v85
	v_mul_f32_e32 v81, v43, v85
	v_fma_f32 v82, v22, v84, -v80
	v_fma_f32 v81, v23, v84, v81
	v_sub_f32_e32 v84, v90, v86
	v_sub_f32_e32 v85, v91, v87
	v_mov_b32_e32 v83, v81
	v_add_f32_e32 v80, v90, v86
	v_add_f32_e32 v81, v91, v87
	v_add_f32_e32 v86, v88, v82
	v_add_f32_e32 v87, v89, v83
	v_sub_f32_e32 v82, v88, v82
	v_sub_f32_e32 v83, v89, v83
	v_add_f32_e32 v88, v80, v86
	v_add_f32_e32 v89, v81, v87
	v_sub_f32_e32 v80, v80, v86
	v_sub_f32_e32 v81, v81, v87
	ds_write_b64 v98, v[88:89] offset:17408
	v_mul_f32_e32 v86, v30, v81
	v_mul_f32_e32 v87, v31, v81
	v_fma_f32 v88, v28, v80, -v86
	v_fma_f32 v81, v29, v80, v87
	v_mov_b32_e32 v89, v81
	v_mul_f32_e32 v80, v32, v85
	v_mul_f32_e32 v81, v33, v85
	ds_write_b64 v98, v[88:89] offset:21760
	v_fma_f32 v86, v24, v84, -v80
	v_fma_f32 v81, v25, v84, v81
	v_mov_b32_e32 v87, v81
	v_mul_f32_e32 v80, v34, v83
	v_mul_f32_e32 v81, v35, v83
	v_fma_f32 v84, v26, v82, -v80
	v_fma_f32 v81, v27, v82, v81
	v_mov_b32_e32 v85, v81
	v_add_f32_e32 v80, v86, v84
;     static __device__ __forceinline__ float sl(float g, float up) { return g * __builtin_amdgcn_rcpf(1.0f + __builtin_amdgcn_exp2f(-1.4426950408889634f * g)) * up; }
; __device__ __forceinline__ float2 cmul(float2 a, float2 b) { return make_float2(a.x * b.x - a.y * b.y, a.x * b.y + a.y * b.x); }
; #define tid ltid()
; template <int LR, bool INV>
; __device__ __forceinline__ void fft_stages(float2 (&x)[1 << LR], const int r, const int s) {
;   constexpr int R = 1 << LR;
; #pragma unroll
;   for (int st = 0; st < LR; ++st) {
;     const int hl = INV ? (1 << st) : (R >> (st + 1));
;     const float fb = (float)r * (0.5f / (float)(hl * s));
;     const float2 wb = make_float2(__builtin_amdgcn_cosf(fb), INV ? __builtin_amdgcn_sinf(fb) : -__builtin_amdgcn_sinf(fb));
; #pragma unroll
;     for (int m = 0; m < R; ++m) {
;       if (m & hl) continue;
;       const int k = m & (hl - 1); const int j = k * (8 / hl);
;       const float2 wc = make_float2(c16(j), INV ? s16(j) : -s16(j));
;       const float2 tw = cmul(wb, wc);
;       if (!INV) { const float2 p = x[m], q = x[m + hl]; x[m] = make_float2(p.x + q.x, p.y + q.y); x[m + hl] = cmul(make_float2(p.x - q.x, p.y - q.y), tw); }
;       else { const float2 p = x[m], q = cmul(x[m + hl], tw); x[m] = make_float2(p.x + q.x, p.y + q.y); x[m + hl] = make_float2(p.x - q.x, p.y - q.y); }
;     }
;   }
; }
; template <int LR, bool INV>
; __device__ __forceinline__ void fft_pass(float2* X, const int N, const int sl, const int tid) {
;   constexpr int R = 1 << LR;
;   const int s = 1 << sl;
;   for (int g = tid; g < (N >> LR); g += NTHR) {
;     const int r = g & (s - 1);
;     const int i0 = ((g >> sl) << (sl + LR)) + r;
;     float2 x[R];
; #pragma unroll
;     for (int m = 0; m < R; ++m) x[m] = X[PIDX(i0 + (m << sl))];
;     fft_stages<LR, INV>(x, r, s);
; #pragma unroll
;     for (int m = 0; m < R; ++m) X[PIDX(i0 + (m << sl))] = x[m];
;   }
	v_add_f32_e32 v81, v87, v85
	v_sub_f32_e32 v82, v86, v84
	v_sub_f32_e32 v83, v87, v85
	ds_write_b64 v98, v[80:81] offset:26112
	v_mul_f32_e32 v80, v30, v83
	v_mul_f32_e32 v81, v31, v83
	v_fma_f32 v84, v28, v82, -v80
	v_fma_f32 v81, v29, v82, v81
	v_mov_b32_e32 v85, v81
	v_mul_f32_e32 v80, v44, v65
	v_mul_f32_e32 v81, v45, v65
	ds_write_b64 v98, v[84:85] offset:30464
	v_fma_f32 v82, v0, v64, -v80
	v_fma_f32 v65, v1, v64, v81
	v_mov_b32_e32 v83, v65
	v_mul_f32_e32 v64, v46, v67
	v_mul_f32_e32 v65, v47, v67
	v_fma_f32 v80, v2, v66, -v64
	v_fma_f32 v65, v3, v66, v65
	v_mov_b32_e32 v81, v65
	v_mul_f32_e32 v64, v48, v69
	v_mul_f32_e32 v65, v49, v69
	v_fma_f32 v66, v4, v68, -v64
	v_fma_f32 v65, v5, v68, v65
	v_mov_b32_e32 v67, v65
	v_mul_f32_e32 v64, v50, v71
	v_mul_f32_e32 v65, v51, v71
	v_fma_f32 v68, v6, v70, -v64
	v_fma_f32 v65, v7, v70, v65
	v_mov_b32_e32 v69, v65
	v_mul_f32_e32 v64, v52, v73
	v_mul_f32_e32 v65, v53, v73
	v_fma_f32 v70, v8, v72, -v64
	v_fma_f32 v65, v9, v72, v65
	v_mov_b32_e32 v71, v65
	v_mul_f32_e32 v64, v54, v75
	v_mul_f32_e32 v65, v55, v75
	v_fma_f32 v72, v10, v74, -v64
	v_fma_f32 v65, v11, v74, v65
	v_mov_b32_e32 v73, v65
	v_mul_f32_e32 v64, v56, v77
	v_mul_f32_e32 v65, v57, v77
	v_fma_f32 v74, v12, v76, -v64
	v_fma_f32 v65, v13, v76, v65
	v_mov_b32_e32 v75, v65
	v_mul_f32_e32 v64, v58, v79
	v_mul_f32_e32 v65, v59, v79
	v_fma_f32 v76, v14, v78, -v64
	v_fma_f32 v65, v15, v78, v65
	v_add_f32_e32 v78, v80, v72
	v_add_f32_e32 v79, v81, v73
	v_mov_b32_e32 v77, v65
	v_add_f32_e32 v64, v82, v70
	v_add_f32_e32 v65, v83, v71
	v_sub_f32_e32 v72, v80, v72
	v_sub_f32_e32 v73, v81, v73
	v_add_f32_e32 v80, v66, v74
	v_add_f32_e32 v81, v67, v75
	v_sub_f32_e32 v66, v66, v74
	v_sub_f32_e32 v67, v67, v75
	v_add_f32_e32 v74, v68, v76
	v_add_f32_e32 v75, v69, v77
	v_sub_f32_e32 v68, v68, v76
	v_sub_f32_e32 v69, v69, v77
	v_add_f32_e32 v76, v64, v80
	v_add_f32_e32 v77, v65, v81
	v_sub_f32_e32 v64, v64, v80
	v_sub_f32_e32 v65, v65, v81
	v_add_f32_e32 v80, v78, v74
	v_add_f32_e32 v81, v79, v75
	v_sub_f32_e32 v74, v78, v74
	v_sub_f32_e32 v75, v79, v75
	v_add_f32_e32 v78, v76, v80
	v_add_f32_e32 v79, v77, v81
	v_sub_f32_e32 v76, v76, v80
	v_sub_f32_e32 v77, v77, v81
	ds_write_b64 v98, v[78:79] offset:34816
	v_mul_f32_e32 v78, v30, v77
	v_mul_f32_e32 v79, v31, v77
	v_sub_f32_e32 v70, v82, v70
	v_sub_f32_e32 v71, v83, v71
	v_fma_f32 v80, v28, v76, -v78
	v_fma_f32 v77, v29, v76, v79
	v_mov_b32_e32 v81, v77
	v_mul_f32_e32 v76, v32, v65
	v_mul_f32_e32 v77, v33, v65
	ds_write_b64 v98, v[80:81] offset:39168
	v_fma_f32 v78, v24, v64, -v76
	v_fma_f32 v65, v25, v64, v77
	v_mov_b32_e32 v79, v65
	v_mul_f32_e32 v64, v34, v75
	v_mul_f32_e32 v65, v35, v75
	v_fma_f32 v76, v26, v74, -v64
	v_fma_f32 v65, v27, v74, v65
	v_mov_b32_e32 v77, v65
	v_add_f32_e32 v64, v78, v76
	v_add_f32_e32 v65, v79, v77
	v_sub_f32_e32 v74, v78, v76
	v_sub_f32_e32 v75, v79, v77
	ds_write_b64 v98, v[64:65] offset:43520
	v_mul_f32_e32 v64, v30, v75
	v_mul_f32_e32 v65, v31, v75
	v_fma_f32 v76, v28, v74, -v64
	v_fma_f32 v65, v29, v74, v65
	v_mov_b32_e32 v77, v65
	v_mul_f32_e32 v64, v36, v71
	v_mul_f32_e32 v65, v37, v71
	ds_write_b64 v98, v[76:77] offset:47872
	v_fma_f32 v74, v16, v70, -v64
	v_fma_f32 v65, v17, v70, v65
	v_mov_b32_e32 v75, v65
	v_mul_f32_e32 v64, v38, v73
	v_mul_f32_e32 v65, v39, v73
	v_fma_f32 v70, v18, v72, -v64
	v_fma_f32 v65, v19, v72, v65
	v_mov_b32_e32 v71, v65
	v_mul_f32_e32 v64, v40, v67
	v_mul_f32_e32 v65, v41, v67
	v_fma_f32 v72, v20, v66, -v64
	v_fma_f32 v65, v21, v66, v65
	v_mov_b32_e32 v73, v65
	v_mul_f32_e32 v64, v42, v69
	v_mul_f32_e32 v65, v43, v69
	v_fma_f32 v66, v22, v68, -v64
	v_fma_f32 v65, v23, v68, v65
	v_sub_f32_e32 v68, v74, v72
	v_sub_f32_e32 v69, v75, v73
	v_mov_b32_e32 v67, v65
	v_add_f32_e32 v64, v74, v72
	v_add_f32_e32 v65, v75, v73
	v_add_f32_e32 v72, v70, v66
	v_add_f32_e32 v73, v71, v67
	v_sub_f32_e32 v66, v70, v66
	v_sub_f32_e32 v67, v71, v67
	v_add_f32_e32 v70, v64, v72
	v_add_f32_e32 v71, v65, v73
	v_sub_f32_e32 v64, v64, v72
	v_sub_f32_e32 v65, v65, v73
	ds_write_b64 v98, v[70:71] offset:52224
	v_mul_f32_e32 v70, v30, v65
	v_mul_f32_e32 v71, v31, v65
	v_fma_f32 v72, v28, v64, -v70
	v_fma_f32 v65, v29, v64, v71
	v_mov_b32_e32 v73, v65
	v_mul_f32_e32 v64, v32, v69
	v_mul_f32_e32 v65, v33, v69
	ds_write_b64 v98, v[72:73] offset:56576
	v_fma_f32 v70, v24, v68, -v64
	v_fma_f32 v65, v25, v68, v65
	v_mov_b32_e32 v71, v65
	v_mul_f32_e32 v64, v34, v67
	v_mul_f32_e32 v65, v35, v67
	v_fma_f32 v68, v26, v66, -v64
	v_fma_f32 v65, v27, v66, v65
	v_mov_b32_e32 v69, v65
	v_add_f32_e32 v64, v70, v68
	v_add_f32_e32 v65, v71, v69
	v_sub_f32_e32 v66, v70, v68
	v_sub_f32_e32 v67, v71, v69
	ds_write_b64 v98, v[64:65] offset:60928
	v_mul_f32_e32 v64, v30, v67
	v_mul_f32_e32 v65, v31, v67
	v_fma_f32 v68, v28, v66, -v64
	v_fma_f32 v65, v29, v66, v65
	v_mov_b32_e32 v69, v65
	ds_write_b64 v98, v[68:69] offset:65280
	s_andn2_b64 exec, exec, s[14:15]
	s_cbranch_execnz .LBB0_656

;     static __device__ __forceinline__ float sl(float g, float up) { return g * __builtin_amdgcn_rcpf(1.0f + __builtin_amdgcn_exp2f(-1.4426950408889634f * g)) * up; }
; #define tid ltid()
; template <int LR, bool INV>
; __device__ __forceinline__ void fft_pass(float2* X, const int N, const int sl, const int tid) {
;     ...
;   for (int g = tid; g < (N >> LR); g += NTHR) {
;     const int r = g & (s - 1);
;     const int i0 = ((g >> sl) << (sl + LR)) + r;
;     float2 x[R];
; #pragma unroll
;     for (int m = 0; m < R; ++m) x[m] = X[PIDX(i0 + (m << sl))];
.LBB0_660:
	v_and_or_b32 v32, v30, s53, v29
	v_ashrrev_i32_e32 v33, 4, v32
	v_lshlrev_b32_e32 v33, 3, v33
	v_lshlrev_b32_e32 v34, 3, v32
	v_add3_u32 v50, s52, v33, v34


;     static __device__ __forceinline__ float sl(float g, float up) { return g * __builtin_amdgcn_rcpf(1.0f + __builtin_amdgcn_exp2f(-1.4426950408889634f * g)) * up; }
; __device__ __forceinline__ float2 cmul(float2 a, float2 b) { return make_float2(a.x * b.x - a.y * b.y, a.x * b.y + a.y * b.x); }
; #define tid ltid()
; template <int LR, bool INV>
; __device__ __forceinline__ void fft_stages(float2 (&x)[1 << LR], const int r, const int s) {
;   constexpr int R = 1 << LR;
; #pragma unroll
;   for (int st = 0; st < LR; ++st) {
;     const int hl = INV ? (1 << st) : (R >> (st + 1));
;     const float fb = (float)r * (0.5f / (float)(hl * s));
;     const float2 wb = make_float2(__builtin_amdgcn_cosf(fb), INV ? __builtin_amdgcn_sinf(fb) : -__builtin_amdgcn_sinf(fb));
; #pragma unroll
;     for (int m = 0; m < R; ++m) {
;       if (m & hl) continue;
;       const int k = m & (hl - 1); const int j = k * (8 / hl);
;       const float2 wc = make_float2(c16(j), INV ? s16(j) : -s16(j));
;       const float2 tw = cmul(wb, wc);
;       if (!INV) { const float2 p = x[m], q = x[m + hl]; x[m] = make_float2(p.x + q.x, p.y + q.y); x[m + hl] = cmul(make_float2(p.x - q.x, p.y - q.y), tw); }
;       else { const float2 p = x[m], q = cmul(x[m + hl], tw); x[m] = make_float2(p.x + q.x, p.y + q.y); x[m + hl] = make_float2(p.x - q.x, p.y - q.y); }
;     }
;   }
; }
; template <int LR, bool INV>
; __device__ __forceinline__ void fft_pass(float2* X, const int N, const int sl, const int tid) {
;   constexpr int R = 1 << LR;
;   const int s = 1 << sl;
;   for (int g = tid; g < (N >> LR); g += NTHR) {
;     const int r = g & (s - 1);
;     const int i0 = ((g >> sl) << (sl + LR)) + r;
;     float2 x[R];
; #pragma unroll
;     for (int m = 0; m < R; ++m) x[m] = X[PIDX(i0 + (m << sl))];
;     fft_stages<LR, INV>(x, r, s);
; #pragma unroll
;     for (int m = 0; m < R; ++m) X[PIDX(i0 + (m << sl))] = x[m];
;   }
	ds_read_b64 v[32:33], v50
	ds_read_b64 v[34:35], v50 offset:544
	ds_read_b64 v[36:37], v50 offset:1088
	ds_read_b64 v[38:39], v50 offset:1632
	ds_read_b64 v[40:41], v50 offset:2176
	ds_read_b64 v[42:43], v50 offset:2720
	ds_read_b64 v[44:45], v50 offset:3264
	ds_read_b64 v[46:47], v50 offset:3808
	v_add_u32_e32 v31, 0x200, v31
	s_waitcnt lgkmcnt(3)
	v_add_f32_e32 v48, v32, v40
	v_add_f32_e32 v49, v33, v41
	v_sub_f32_e32 v32, v32, v40
	v_sub_f32_e32 v33, v33, v41
	s_waitcnt lgkmcnt(2)
	v_add_f32_e32 v40, v34, v42
	v_add_f32_e32 v41, v35, v43
	v_sub_f32_e32 v34, v34, v42
	v_sub_f32_e32 v35, v35, v43
	s_waitcnt lgkmcnt(1)
	v_add_f32_e32 v42, v36, v44
	v_add_f32_e32 v43, v37, v45
	v_sub_f32_e32 v36, v36, v44
	v_sub_f32_e32 v37, v37, v45
	s_waitcnt lgkmcnt(0)
	v_add_f32_e32 v44, v38, v46
	v_add_f32_e32 v45, v39, v47
	v_sub_f32_e32 v38, v38, v46
	v_sub_f32_e32 v39, v39, v47
	v_add_f32_e32 v46, v48, v42
	v_add_f32_e32 v47, v49, v43
	v_sub_f32_e32 v42, v48, v42
	v_sub_f32_e32 v43, v49, v43
	v_add_f32_e32 v48, v40, v44
	v_add_f32_e32 v49, v41, v45
	v_sub_f32_e32 v40, v40, v44
	v_sub_f32_e32 v41, v41, v45
	v_add_f32_e32 v44, v46, v48
	v_add_f32_e32 v45, v47, v49
	v_sub_f32_e32 v46, v46, v48
	v_sub_f32_e32 v47, v47, v49
	ds_write_b64 v50, v[44:45]
	v_mul_f32_e32 v44, v14, v47
	v_mul_f32_e32 v45, v15, v47
	v_cmp_le_i32_e64 s[40:41], s19, v31
	v_fma_f32 v48, v12, v46, -v44
	v_fma_f32 v45, v13, v46, v45
	v_add_u32_e32 v30, 0x1000, v30
	v_mov_b32_e32 v49, v45
	v_mul_f32_e32 v44, v16, v43
	v_mul_f32_e32 v45, v17, v43
	ds_write_b64 v50, v[48:49] offset:544
	v_fma_f32 v46, v8, v42, -v44
	v_fma_f32 v43, v9, v42, v45
	s_or_b64 s[14:15], s[40:41], s[14:15]
	v_mov_b32_e32 v47, v43
	v_mul_f32_e32 v42, v18, v41
	v_mul_f32_e32 v43, v19, v41
	v_fma_f32 v44, v10, v40, -v42
	v_fma_f32 v41, v11, v40, v43
	v_mov_b32_e32 v45, v41
	v_add_f32_e32 v40, v46, v44
	v_add_f32_e32 v41, v47, v45
	v_sub_f32_e32 v42, v46, v44
	v_sub_f32_e32 v43, v47, v45
	ds_write_b64 v50, v[40:41] offset:1088
	v_mul_f32_e32 v40, v14, v43
	v_mul_f32_e32 v41, v15, v43
	v_fma_f32 v44, v12, v42, -v40
	v_fma_f32 v41, v13, v42, v41
	v_mov_b32_e32 v45, v41
	v_mul_f32_e32 v40, v20, v33
	v_mul_f32_e32 v41, v21, v33
	ds_write_b64 v50, v[44:45] offset:1632
	v_fma_f32 v42, v0, v32, -v40
	v_fma_f32 v33, v1, v32, v41
	v_mov_b32_e32 v43, v33
	v_mul_f32_e32 v32, v22, v35
	v_mul_f32_e32 v33, v23, v35
	v_fma_f32 v40, v2, v34, -v32
	v_fma_f32 v33, v3, v34, v33
	v_mov_b32_e32 v41, v33
	v_mul_f32_e32 v32, v24, v37
	v_mul_f32_e32 v33, v25, v37
	v_fma_f32 v34, v4, v36, -v32
	v_fma_f32 v33, v5, v36, v33
	v_mov_b32_e32 v35, v33
	v_mul_f32_e32 v32, v26, v39
	v_mul_f32_e32 v33, v27, v39
	v_fma_f32 v36, v6, v38, -v32
	v_fma_f32 v33, v7, v38, v33
	v_mov_b32_e32 v37, v33
	v_add_f32_e32 v32, v42, v34
	v_add_f32_e32 v33, v43, v35
	v_add_f32_e32 v38, v40, v36
	v_add_f32_e32 v39, v41, v37
	v_sub_f32_e32 v36, v40, v36
	v_sub_f32_e32 v37, v41, v37
	v_add_f32_e32 v40, v32, v38
	v_add_f32_e32 v41, v33, v39
	v_sub_f32_e32 v32, v32, v38
	v_sub_f32_e32 v33, v33, v39
	v_sub_f32_e32 v34, v42, v34
	v_sub_f32_e32 v35, v43, v35
	v_mul_f32_e32 v38, v14, v33
	v_mul_f32_e32 v39, v15, v33
	ds_write_b64 v50, v[40:41] offset:2176
	v_fma_f32 v40, v12, v32, -v38
	v_fma_f32 v33, v13, v32, v39
	v_mov_b32_e32 v41, v33
	v_mul_f32_e32 v32, v16, v35
	v_mul_f32_e32 v33, v17, v35
	ds_write_b64 v50, v[40:41] offset:2720
	v_fma_f32 v38, v8, v34, -v32
	v_fma_f32 v33, v9, v34, v33
	v_mov_b32_e32 v39, v33
	v_mul_f32_e32 v32, v18, v37
	v_mul_f32_e32 v33, v19, v37
	v_fma_f32 v34, v10, v36, -v32
	v_fma_f32 v33, v11, v36, v33
	v_mov_b32_e32 v35, v33
	v_add_f32_e32 v32, v38, v34
	v_add_f32_e32 v33, v39, v35
	v_sub_f32_e32 v34, v38, v34
	v_sub_f32_e32 v35, v39, v35
	ds_write_b64 v50, v[32:33] offset:3264
	v_mul_f32_e32 v32, v14, v35
	v_mul_f32_e32 v33, v15, v35
	v_fma_f32 v36, v12, v34, -v32
	v_fma_f32 v32, v12, v34, v32
	v_fma_f32 v33, v13, v34, v33
	v_mov_b32_e32 v37, v33
	ds_write_b64 v50, v[36:37] offset:3808
	s_andn2_b64 exec, exec, s[14:15]
	s_cbranch_execnz .LBB0_660

;     static __device__ __forceinline__ float sl(float g, float up) { return g * __builtin_amdgcn_rcpf(1.0f + __builtin_amdgcn_exp2f(-1.4426950408889634f * g)) * up; }
; #define tid ltid()
; template <int LR, bool INV>
; __device__ __forceinline__ void fft_pass(float2* X, const int N, const int sl, const int tid) {
;     ...
;   for (int g = tid; g < (N >> LR); g += NTHR) {
;     const int r = g & (s - 1);
;     const int i0 = ((g >> sl) << (sl + LR)) + r;
;     float2 x[R];
; #pragma unroll
;     for (int m = 0; m < R; ++m) x[m] = X[PIDX(i0 + (m << sl))];
.LBB0_663:
	v_and_b32_e32 v32, 0xffffffc0, v30
	v_or_b32_e32 v33, v32, v29
	v_ashrrev_i32_e32 v34, 1, v32
	v_lshlrev_b32_e32 v33, 3, v33
	v_add3_u32 v52, s52, v34, v33
	v_or_b32_e32 v34, 16, v32
	v_ashrrev_i32_e32 v34, 4, v34
	v_lshlrev_b32_e32 v34, 3, v34
	v_add3_u32 v53, s52, v34, v33


;     static __device__ __forceinline__ float sl(float g, float up) { return g * __builtin_amdgcn_rcpf(1.0f + __builtin_amdgcn_exp2f(-1.4426950408889634f * g)) * up; }
; __device__ __forceinline__ float2 cmul(float2 a, float2 b) { return make_float2(a.x * b.x - a.y * b.y, a.x * b.y + a.y * b.x); }
; #define tid ltid()
; template <int LR, bool INV>
; __device__ __forceinline__ void fft_stages(float2 (&x)[1 << LR], const int r, const int s) {
;   constexpr int R = 1 << LR;
; #pragma unroll
;   for (int st = 0; st < LR; ++st) {
;     const int hl = INV ? (1 << st) : (R >> (st + 1));
;     const float fb = (float)r * (0.5f / (float)(hl * s));
;     const float2 wb = make_float2(__builtin_amdgcn_cosf(fb), INV ? __builtin_amdgcn_sinf(fb) : -__builtin_amdgcn_sinf(fb));
; #pragma unroll
;     for (int m = 0; m < R; ++m) {
;       if (m & hl) continue;
;       const int k = m & (hl - 1); const int j = k * (8 / hl);
;       const float2 wc = make_float2(c16(j), INV ? s16(j) : -s16(j));
;       const float2 tw = cmul(wb, wc);
;       if (!INV) { const float2 p = x[m], q = x[m + hl]; x[m] = make_float2(p.x + q.x, p.y + q.y); x[m + hl] = cmul(make_float2(p.x - q.x, p.y - q.y), tw); }
;       else { const float2 p = x[m], q = cmul(x[m + hl], tw); x[m] = make_float2(p.x + q.x, p.y + q.y); x[m + hl] = make_float2(p.x - q.x, p.y - q.y); }
;     }
;   }
; }
; template <int LR, bool INV>
; __device__ __forceinline__ void fft_pass(float2* X, const int N, const int sl, const int tid) {
;   constexpr int R = 1 << LR;
;   const int s = 1 << sl;
;   for (int g = tid; g < (N >> LR); g += NTHR) {
;     const int r = g & (s - 1);
;     const int i0 = ((g >> sl) << (sl + LR)) + r;
;     float2 x[R];
; #pragma unroll
;     for (int m = 0; m < R; ++m) x[m] = X[PIDX(i0 + (m << sl))];
;     fft_stages<LR, INV>(x, r, s);
; #pragma unroll
;     for (int m = 0; m < R; ++m) X[PIDX(i0 + (m << sl))] = x[m];
;   }
	ds_read2_b64 v[32:35], v52 offset1:8
	ds_read2_b64 v[36:39], v53 offset0:16 offset1:24
	ds_read2_b64 v[40:43], v53 offset0:33 offset1:41
	ds_read2_b64 v[44:47], v53 offset0:50 offset1:58
	v_add_u32_e32 v31, 0x200, v31
	v_cmp_le_i32_e64 s[40:41], s19, v31
	v_add_u32_e32 v30, 0x1000, v30
	s_waitcnt lgkmcnt(1)
	v_add_f32_e32 v48, v32, v40
	v_add_f32_e32 v49, v33, v41
	v_sub_f32_e32 v32, v32, v40
	v_sub_f32_e32 v33, v33, v41
	v_add_f32_e32 v40, v34, v42
	v_add_f32_e32 v41, v35, v43
	v_sub_f32_e32 v34, v34, v42
	v_sub_f32_e32 v35, v35, v43
	s_waitcnt lgkmcnt(0)
	v_add_f32_e32 v42, v36, v44
	v_add_f32_e32 v43, v37, v45
	v_sub_f32_e32 v36, v36, v44
	v_sub_f32_e32 v37, v37, v45
	v_add_f32_e32 v44, v38, v46
	v_add_f32_e32 v45, v39, v47
	v_sub_f32_e32 v38, v38, v46
	v_sub_f32_e32 v39, v39, v47
	v_add_f32_e32 v46, v48, v42
	v_add_f32_e32 v47, v49, v43
	v_sub_f32_e32 v42, v48, v42
	v_sub_f32_e32 v43, v49, v43
	v_add_f32_e32 v48, v40, v44
	v_add_f32_e32 v49, v41, v45
	v_sub_f32_e32 v40, v40, v44
	v_sub_f32_e32 v41, v41, v45
	v_add_f32_e32 v44, v46, v48
	v_add_f32_e32 v45, v47, v49
	v_sub_f32_e32 v46, v46, v48
	v_sub_f32_e32 v47, v47, v49
	s_or_b64 s[14:15], s[40:41], s[14:15]
	v_mul_f32_e32 v48, v14, v47
	v_mul_f32_e32 v49, v15, v47
	v_fma_f32 v50, v12, v46, -v48
	v_fma_f32 v47, v13, v46, v49
	v_mov_b32_e32 v51, v47
	ds_write2_b64 v52, v[44:45], v[50:51] offset1:8
	v_mul_f32_e32 v44, v16, v43
	v_mul_f32_e32 v45, v17, v43
	v_fma_f32 v46, v8, v42, -v44
	v_fma_f32 v43, v9, v42, v45
	v_mov_b32_e32 v47, v43
	v_mul_f32_e32 v42, v18, v41
	v_mul_f32_e32 v43, v19, v41
	v_fma_f32 v44, v10, v40, -v42
	v_fma_f32 v41, v11, v40, v43
	v_mov_b32_e32 v45, v41
	v_sub_f32_e32 v42, v46, v44
	v_sub_f32_e32 v43, v47, v45
	v_add_f32_e32 v40, v46, v44
	v_add_f32_e32 v41, v47, v45
	v_mul_f32_e32 v44, v14, v43
	v_mul_f32_e32 v45, v15, v43
	v_fma_f32 v46, v12, v42, -v44
	v_fma_f32 v43, v13, v42, v45
	v_mov_b32_e32 v47, v43
	ds_write2_b64 v53, v[40:41], v[46:47] offset0:16 offset1:24
	v_mul_f32_e32 v40, v20, v33
	v_mul_f32_e32 v41, v21, v33
	v_fma_f32 v42, v0, v32, -v40
	v_fma_f32 v33, v1, v32, v41
	v_mov_b32_e32 v43, v33
	v_mul_f32_e32 v32, v22, v35
	v_mul_f32_e32 v33, v23, v35
	v_fma_f32 v40, v2, v34, -v32
	v_fma_f32 v33, v3, v34, v33
	v_mov_b32_e32 v41, v33
	v_mul_f32_e32 v32, v24, v37
	v_mul_f32_e32 v33, v25, v37
	v_fma_f32 v34, v4, v36, -v32
	v_fma_f32 v33, v5, v36, v33
	v_mov_b32_e32 v35, v33
	v_mul_f32_e32 v32, v26, v39
	v_mul_f32_e32 v33, v27, v39
	v_fma_f32 v36, v6, v38, -v32
	v_fma_f32 v33, v7, v38, v33
	v_mov_b32_e32 v37, v33
	v_add_f32_e32 v32, v42, v34
	v_add_f32_e32 v33, v43, v35
	v_add_f32_e32 v38, v40, v36
	v_add_f32_e32 v39, v41, v37
	v_sub_f32_e32 v36, v40, v36
	v_sub_f32_e32 v37, v41, v37
	v_add_f32_e32 v40, v32, v38
	v_add_f32_e32 v41, v33, v39
	v_sub_f32_e32 v32, v32, v38
	v_sub_f32_e32 v33, v33, v39
	v_sub_f32_e32 v34, v42, v34
	v_sub_f32_e32 v35, v43, v35
	v_mul_f32_e32 v38, v14, v33
	v_mul_f32_e32 v39, v15, v33
	v_fma_f32 v42, v12, v32, -v38
	v_fma_f32 v33, v13, v32, v39
	v_mov_b32_e32 v43, v33
	v_mul_f32_e32 v32, v16, v35
	v_mul_f32_e32 v33, v17, v35
	ds_write2_b64 v53, v[40:41], v[42:43] offset0:33 offset1:41
	v_fma_f32 v38, v8, v34, -v32
	v_fma_f32 v33, v9, v34, v33
	v_mov_b32_e32 v39, v33
	v_mul_f32_e32 v32, v18, v37
	v_mul_f32_e32 v33, v19, v37
	v_fma_f32 v34, v10, v36, -v32
	v_fma_f32 v33, v11, v36, v33
	v_mov_b32_e32 v35, v33
	v_add_f32_e32 v32, v38, v34
	v_add_f32_e32 v33, v39, v35
	v_sub_f32_e32 v34, v38, v34
	v_sub_f32_e32 v35, v39, v35
	v_mul_f32_e32 v36, v14, v35
	v_mul_f32_e32 v37, v15, v35
	v_fma_f32 v38, v12, v34, -v36
	v_fma_f32 v35, v13, v34, v37
	v_fma_f32 v34, v12, v34, v36
	v_mov_b32_e32 v39, v35
	ds_write2_b64 v53, v[32:33], v[38:39] offset0:50 offset1:58
	s_andn2_b64 exec, exec, s[14:15]
	s_cbranch_execnz .LBB0_663

;     static __device__ __forceinline__ float sl(float g, float up) { return g * __builtin_amdgcn_rcpf(1.0f + __builtin_amdgcn_exp2f(-1.4426950408889634f * g)) * up; }
; #define tid ltid()
; template <int LR, bool INV>
; __device__ __forceinline__ void fft_pass(float2* X, const int N, const int sl, const int tid) {
;     ...
;   for (int g = tid; g < (N >> LR); g += NTHR) {
;     const int r = g & (s - 1);
;     const int i0 = ((g >> sl) << (sl + LR)) + r;
;     float2 x[R];
; #pragma unroll
;     for (int m = 0; m < R; ++m) x[m] = X[PIDX(i0 + (m << sl))];
.LBB0_675:
	v_and_or_b32 v33, v32, s53, v31
	v_ashrrev_i32_e32 v34, 4, v33
	v_lshlrev_b32_e32 v34, 3, v34
	v_lshlrev_b32_e32 v35, 3, v33
	v_add3_u32 v52, 0, v34, v35


;     static __device__ __forceinline__ float sl(float g, float up) { return g * __builtin_amdgcn_rcpf(1.0f + __builtin_amdgcn_exp2f(-1.4426950408889634f * g)) * up; }
; #define tid ltid()
; template <int LR, bool INV>
; __device__ __forceinline__ void fft_pass(float2* X, const int N, const int sl, const int tid) {
;     ...
;   for (int g = tid; g < (N >> LR); g += NTHR) {
;     const int r = g & (s - 1);
;     const int i0 = ((g >> sl) << (sl + LR)) + r;
;     float2 x[R];
; #pragma unroll
;     for (int m = 0; m < R; ++m) x[m] = X[PIDX(i0 + (m << sl))];
	v_or_b32_e32 v33, 0x1c0, v33

;     static __device__ __forceinline__ float sl(float g, float up) { return g * __builtin_amdgcn_rcpf(1.0f + __builtin_amdgcn_exp2f(-1.4426950408889634f * g)) * up; }
; #define tid ltid()
; template <int LR, bool INV>
; __device__ __forceinline__ void fft_pass(float2* X, const int N, const int sl, const int tid) {
;     ...
;   for (int g = tid; g < (N >> LR); g += NTHR) {
;     const int r = g & (s - 1);
;     const int i0 = ((g >> sl) << (sl + LR)) + r;
;     float2 x[R];
; #pragma unroll
;     for (int m = 0; m < R; ++m) x[m] = X[PIDX(i0 + (m << sl))];
	v_ashrrev_i32_e32 v33, 4, v33

;     static __device__ __forceinline__ float sl(float g, float up) { return g * __builtin_amdgcn_rcpf(1.0f + __builtin_amdgcn_exp2f(-1.4426950408889634f * g)) * up; }
; #define tid ltid()
; template <int LR, bool INV>
; __device__ __forceinline__ void fft_pass(float2* X, const int N, const int sl, const int tid) {
;     ...
;   for (int g = tid; g < (N >> LR); g += NTHR) {
;     const int r = g & (s - 1);
;     const int i0 = ((g >> sl) << (sl + LR)) + r;
;     float2 x[R];
; #pragma unroll
;     for (int m = 0; m < R; ++m) x[m] = X[PIDX(i0 + (m << sl))];
	v_lshlrev_b32_e32 v33, 3, v33

;     static __device__ __forceinline__ float sl(float g, float up) { return g * __builtin_amdgcn_rcpf(1.0f + __builtin_amdgcn_exp2f(-1.4426950408889634f * g)) * up; }
; __device__ __forceinline__ float2 cmul(float2 a, float2 b) { return make_float2(a.x * b.x - a.y * b.y, a.x * b.y + a.y * b.x); }
; #define tid ltid()
; template <int LR, bool INV>
; __device__ __forceinline__ void fft_stages(float2 (&x)[1 << LR], const int r, const int s) {
;   constexpr int R = 1 << LR;
; #pragma unroll
;   for (int st = 0; st < LR; ++st) {
;     const int hl = INV ? (1 << st) : (R >> (st + 1));
;     const float fb = (float)r * (0.5f / (float)(hl * s));
;     const float2 wb = make_float2(__builtin_amdgcn_cosf(fb), INV ? __builtin_amdgcn_sinf(fb) : -__builtin_amdgcn_sinf(fb));
; #pragma unroll
;     for (int m = 0; m < R; ++m) {
;       if (m & hl) continue;
;       const int k = m & (hl - 1); const int j = k * (8 / hl);
;       const float2 wc = make_float2(c16(j), INV ? s16(j) : -s16(j));
;       const float2 tw = cmul(wb, wc);
;       if (!INV) { const float2 p = x[m], q = x[m + hl]; x[m] = make_float2(p.x + q.x, p.y + q.y); x[m + hl] = cmul(make_float2(p.x - q.x, p.y - q.y), tw); }
;       else { const float2 p = x[m], q = cmul(x[m + hl], tw); x[m] = make_float2(p.x + q.x, p.y + q.y); x[m + hl] = make_float2(p.x - q.x, p.y - q.y); }
;     }
;   }
; }
; template <int LR, bool INV>
; __device__ __forceinline__ void fft_pass(float2* X, const int N, const int sl, const int tid) {
;   constexpr int R = 1 << LR;
;   const int s = 1 << sl;
;   for (int g = tid; g < (N >> LR); g += NTHR) {
;     const int r = g & (s - 1);
;     const int i0 = ((g >> sl) << (sl + LR)) + r;
;     float2 x[R];
; #pragma unroll
;     for (int m = 0; m < R; ++m) x[m] = X[PIDX(i0 + (m << sl))];
;     fft_stages<LR, INV>(x, r, s);
; #pragma unroll
;     for (int m = 0; m < R; ++m) X[PIDX(i0 + (m << sl))] = x[m];
;   }
	v_add3_u32 v33, 0, v33, v35
	ds_read_b64 v[34:35], v52
	ds_read_b64 v[36:37], v52 offset:544
	ds_read_b64 v[38:39], v52 offset:1088
	ds_read_b64 v[40:41], v52 offset:1632
	ds_read_b64 v[42:43], v52 offset:2176
	ds_read_b64 v[44:45], v52 offset:2720
	ds_read_b64 v[46:47], v52 offset:3264
	ds_read_b64 v[48:49], v52 offset:3808
	v_add_u32_e32 v30, 0x200, v30
	s_waitcnt lgkmcnt(3)
	v_add_f32_e32 v50, v34, v42
	v_add_f32_e32 v51, v35, v43
	v_sub_f32_e32 v34, v34, v42
	v_sub_f32_e32 v35, v35, v43
	s_waitcnt lgkmcnt(2)
	v_add_f32_e32 v42, v36, v44
	v_add_f32_e32 v43, v37, v45
	v_sub_f32_e32 v36, v36, v44
	v_sub_f32_e32 v37, v37, v45
	s_waitcnt lgkmcnt(1)
	v_add_f32_e32 v44, v38, v46
	v_add_f32_e32 v45, v39, v47
	v_sub_f32_e32 v38, v38, v46
	v_sub_f32_e32 v39, v39, v47
	s_waitcnt lgkmcnt(0)
	v_add_f32_e32 v46, v40, v48
	v_add_f32_e32 v47, v41, v49
	v_sub_f32_e32 v40, v40, v48
	v_sub_f32_e32 v41, v41, v49
	v_add_f32_e32 v48, v50, v44
	v_add_f32_e32 v49, v51, v45
	v_sub_f32_e32 v44, v50, v44
	v_sub_f32_e32 v45, v51, v45
	v_add_f32_e32 v50, v42, v46
	v_add_f32_e32 v51, v43, v47
	v_sub_f32_e32 v42, v42, v46
	v_sub_f32_e32 v43, v43, v47
	v_add_f32_e32 v46, v48, v50
	v_add_f32_e32 v47, v49, v51
	v_sub_f32_e32 v48, v48, v50
	v_sub_f32_e32 v49, v49, v51
	ds_write_b64 v52, v[46:47]
	v_mul_f32_e32 v46, v16, v49
	v_mul_f32_e32 v47, v17, v49
	v_cmp_le_i32_e32 vcc, s21, v30
	v_fma_f32 v50, v14, v48, -v46
	v_fma_f32 v47, v15, v48, v47
	v_add_u32_e32 v32, 0x1000, v32
	v_mov_b32_e32 v51, v47
	v_mul_f32_e32 v46, v18, v45
	v_mul_f32_e32 v47, v19, v45
	ds_write_b64 v52, v[50:51] offset:544
	v_fma_f32 v48, v10, v44, -v46
	v_fma_f32 v45, v11, v44, v47
	s_or_b64 s[14:15], vcc, s[14:15]
	v_mov_b32_e32 v49, v45
	v_mul_f32_e32 v44, v20, v43
	v_mul_f32_e32 v45, v21, v43
	v_fma_f32 v46, v12, v42, -v44
	v_fma_f32 v43, v13, v42, v45
	v_mov_b32_e32 v47, v43
	v_add_f32_e32 v42, v48, v46
	v_add_f32_e32 v43, v49, v47
	v_sub_f32_e32 v44, v48, v46
	v_sub_f32_e32 v45, v49, v47
	ds_write_b64 v52, v[42:43] offset:1088
	v_mul_f32_e32 v42, v16, v45
	v_mul_f32_e32 v43, v17, v45
	v_fma_f32 v46, v14, v44, -v42
	v_fma_f32 v43, v15, v44, v43
	v_mov_b32_e32 v47, v43
	v_mul_f32_e32 v42, v22, v35
	v_mul_f32_e32 v43, v23, v35
	ds_write_b64 v52, v[46:47] offset:1632
	v_fma_f32 v44, v2, v34, -v42
	v_fma_f32 v35, v3, v34, v43
	v_mov_b32_e32 v45, v35
	v_mul_f32_e32 v34, v24, v37
	v_mul_f32_e32 v35, v25, v37
	v_fma_f32 v42, v4, v36, -v34
	v_fma_f32 v35, v5, v36, v35
	v_mov_b32_e32 v43, v35
	v_mul_f32_e32 v34, v26, v39
	v_mul_f32_e32 v35, v27, v39
	v_fma_f32 v36, v6, v38, -v34
	v_fma_f32 v35, v7, v38, v35
	v_mov_b32_e32 v37, v35
	v_mul_f32_e32 v34, v28, v41
	v_mul_f32_e32 v35, v29, v41
	v_fma_f32 v38, v8, v40, -v34
	v_fma_f32 v35, v9, v40, v35
	v_mov_b32_e32 v39, v35
	v_add_f32_e32 v34, v44, v36
	v_add_f32_e32 v35, v45, v37
	v_add_f32_e32 v40, v42, v38
	v_add_f32_e32 v41, v43, v39
	v_sub_f32_e32 v38, v42, v38
	v_sub_f32_e32 v39, v43, v39
	v_add_f32_e32 v42, v34, v40
	v_add_f32_e32 v43, v35, v41
	v_sub_f32_e32 v34, v34, v40
	v_sub_f32_e32 v35, v35, v41
	v_sub_f32_e32 v36, v44, v36
	v_sub_f32_e32 v37, v45, v37
	v_mul_f32_e32 v40, v16, v35
	v_mul_f32_e32 v41, v17, v35
	ds_write_b64 v52, v[42:43] offset:2176
	v_fma_f32 v42, v14, v34, -v40
	v_fma_f32 v35, v15, v34, v41
	v_mov_b32_e32 v43, v35
	v_mul_f32_e32 v34, v18, v37
	v_mul_f32_e32 v35, v19, v37
	ds_write_b64 v52, v[42:43] offset:2720
	v_fma_f32 v40, v10, v36, -v34
	v_fma_f32 v35, v11, v36, v35
	v_mov_b32_e32 v41, v35
	v_mul_f32_e32 v34, v20, v39
	v_mul_f32_e32 v35, v21, v39
	v_fma_f32 v36, v12, v38, -v34
	v_fma_f32 v35, v13, v38, v35
	v_mov_b32_e32 v37, v35
	v_add_f32_e32 v34, v40, v36
	v_add_f32_e32 v35, v41, v37
	v_sub_f32_e32 v36, v40, v36
	v_sub_f32_e32 v37, v41, v37
	ds_write_b64 v52, v[34:35] offset:3264
	v_mul_f32_e32 v34, v16, v37
	v_mul_f32_e32 v35, v17, v37
	v_fma_f32 v38, v14, v36, -v34
	v_fma_f32 v34, v14, v36, v34
	v_fma_f32 v35, v15, v36, v35
	v_mov_b32_e32 v39, v35
	ds_write_b64 v52, v[38:39] offset:3808
	s_andn2_b64 exec, exec, s[14:15]
	s_cbranch_execnz .LBB0_675

;     static __device__ __forceinline__ float sl(float g, float up) { return g * __builtin_amdgcn_rcpf(1.0f + __builtin_amdgcn_exp2f(-1.4426950408889634f * g)) * up; }
; #define tid ltid()
; template <int LR, bool INV>
; __device__ __forceinline__ void fft_pass(float2* X, const int N, const int sl, const int tid) {
;     ...
;   for (int g = tid; g < (N >> LR); g += NTHR) {
;     const int r = g & (s - 1);
;     const int i0 = ((g >> sl) << (sl + LR)) + r;
;     float2 x[R];
; #pragma unroll
;     for (int m = 0; m < R; ++m) x[m] = X[PIDX(i0 + (m << sl))];
.LBB0_678:
	v_and_b32_e32 v33, 0xffffffc0, v32
	v_or_b32_e32 v34, v33, v31
	v_ashrrev_i32_e32 v35, 1, v33
	v_lshlrev_b32_e32 v34, 3, v34
	v_add3_u32 v54, 0, v35, v34
	v_or_b32_e32 v35, 16, v33
	v_ashrrev_i32_e32 v35, 4, v35
	v_lshlrev_b32_e32 v35, 3, v35
	v_add3_u32 v55, 0, v35, v34

;     static __device__ __forceinline__ float sl(float g, float up) { return g * __builtin_amdgcn_rcpf(1.0f + __builtin_amdgcn_exp2f(-1.4426950408889634f * g)) * up; }
; #define tid ltid()
; template <int LR, bool INV>
; __device__ __forceinline__ void fft_pass(float2* X, const int N, const int sl, const int tid) {
;     ...
;   for (int g = tid; g < (N >> LR); g += NTHR) {
;     const int r = g & (s - 1);
;     const int i0 = ((g >> sl) << (sl + LR)) + r;
;     float2 x[R];
; #pragma unroll
;     for (int m = 0; m < R; ++m) x[m] = X[PIDX(i0 + (m << sl))];
	v_or_b32_e32 v33, 48, v33

;     static __device__ __forceinline__ float sl(float g, float up) { return g * __builtin_amdgcn_rcpf(1.0f + __builtin_amdgcn_exp2f(-1.4426950408889634f * g)) * up; }
; #define tid ltid()
; template <int LR, bool INV>
; __device__ __forceinline__ void fft_pass(float2* X, const int N, const int sl, const int tid) {
;     ...
;   for (int g = tid; g < (N >> LR); g += NTHR) {
;     const int r = g & (s - 1);
;     const int i0 = ((g >> sl) << (sl + LR)) + r;
;     float2 x[R];
; #pragma unroll
;     for (int m = 0; m < R; ++m) x[m] = X[PIDX(i0 + (m << sl))];
	v_ashrrev_i32_e32 v33, 4, v33

;     static __device__ __forceinline__ float sl(float g, float up) { return g * __builtin_amdgcn_rcpf(1.0f + __builtin_amdgcn_exp2f(-1.4426950408889634f * g)) * up; }
; #define tid ltid()
; template <int LR, bool INV>
; __device__ __forceinline__ void fft_pass(float2* X, const int N, const int sl, const int tid) {
;     ...
;   for (int g = tid; g < (N >> LR); g += NTHR) {
;     const int r = g & (s - 1);
;     const int i0 = ((g >> sl) << (sl + LR)) + r;
;     float2 x[R];
; #pragma unroll
;     for (int m = 0; m < R; ++m) x[m] = X[PIDX(i0 + (m << sl))];
	v_lshlrev_b32_e32 v33, 3, v33

;     static __device__ __forceinline__ float sl(float g, float up) { return g * __builtin_amdgcn_rcpf(1.0f + __builtin_amdgcn_exp2f(-1.4426950408889634f * g)) * up; }
; __device__ __forceinline__ float2 cmul(float2 a, float2 b) { return make_float2(a.x * b.x - a.y * b.y, a.x * b.y + a.y * b.x); }
; #define tid ltid()
; template <int LR, bool INV>
; __device__ __forceinline__ void fft_stages(float2 (&x)[1 << LR], const int r, const int s) {
;   constexpr int R = 1 << LR;
; #pragma unroll
;   for (int st = 0; st < LR; ++st) {
;     const int hl = INV ? (1 << st) : (R >> (st + 1));
;     const float fb = (float)r * (0.5f / (float)(hl * s));
;     const float2 wb = make_float2(__builtin_amdgcn_cosf(fb), INV ? __builtin_amdgcn_sinf(fb) : -__builtin_amdgcn_sinf(fb));
; #pragma unroll
;     for (int m = 0; m < R; ++m) {
;       if (m & hl) continue;
;       const int k = m & (hl - 1); const int j = k * (8 / hl);
;       const float2 wc = make_float2(c16(j), INV ? s16(j) : -s16(j));
;       const float2 tw = cmul(wb, wc);
;       if (!INV) { const float2 p = x[m], q = x[m + hl]; x[m] = make_float2(p.x + q.x, p.y + q.y); x[m + hl] = cmul(make_float2(p.x - q.x, p.y - q.y), tw); }
;       else { const float2 p = x[m], q = cmul(x[m + hl], tw); x[m] = make_float2(p.x + q.x, p.y + q.y); x[m + hl] = make_float2(p.x - q.x, p.y - q.y); }
;     }
;   }
; }
; template <int LR, bool INV>
; __device__ __forceinline__ void fft_pass(float2* X, const int N, const int sl, const int tid) {
;   constexpr int R = 1 << LR;
;   const int s = 1 << sl;
;   for (int g = tid; g < (N >> LR); g += NTHR) {
;     const int r = g & (s - 1);
;     const int i0 = ((g >> sl) << (sl + LR)) + r;
;     float2 x[R];
; #pragma unroll
;     for (int m = 0; m < R; ++m) x[m] = X[PIDX(i0 + (m << sl))];
;     fft_stages<LR, INV>(x, r, s);
; #pragma unroll
;     for (int m = 0; m < R; ++m) X[PIDX(i0 + (m << sl))] = x[m];
;   }
	v_add3_u32 v33, 0, v33, v34
	ds_read2_b64 v[34:37], v54 offset1:8
	ds_read2_b64 v[38:41], v55 offset0:16 offset1:24
	ds_read2_b64 v[42:45], v55 offset0:33 offset1:41
	ds_read2_b64 v[46:49], v55 offset0:50 offset1:58
	v_add_u32_e32 v30, 0x200, v30
	v_cmp_le_i32_e32 vcc, s21, v30
	v_add_u32_e32 v32, 0x1000, v32
	s_waitcnt lgkmcnt(1)
	v_add_f32_e32 v50, v34, v42
	v_add_f32_e32 v51, v35, v43
	v_sub_f32_e32 v34, v34, v42
	v_sub_f32_e32 v35, v35, v43
	v_add_f32_e32 v42, v36, v44
	v_add_f32_e32 v43, v37, v45
	v_sub_f32_e32 v36, v36, v44
	v_sub_f32_e32 v37, v37, v45
	s_waitcnt lgkmcnt(0)
	v_add_f32_e32 v44, v38, v46
	v_add_f32_e32 v45, v39, v47
	v_sub_f32_e32 v38, v38, v46
	v_sub_f32_e32 v39, v39, v47
	v_add_f32_e32 v46, v40, v48
	v_add_f32_e32 v47, v41, v49
	v_sub_f32_e32 v40, v40, v48
	v_sub_f32_e32 v41, v41, v49
	v_add_f32_e32 v48, v50, v44
	v_add_f32_e32 v49, v51, v45
	v_sub_f32_e32 v44, v50, v44
	v_sub_f32_e32 v45, v51, v45
	v_add_f32_e32 v50, v42, v46
	v_add_f32_e32 v51, v43, v47
	v_sub_f32_e32 v42, v42, v46
	v_sub_f32_e32 v43, v43, v47
	v_add_f32_e32 v46, v48, v50
	v_add_f32_e32 v47, v49, v51
	v_sub_f32_e32 v48, v48, v50
	v_sub_f32_e32 v49, v49, v51
	s_or_b64 s[14:15], vcc, s[14:15]
	v_mul_f32_e32 v50, v16, v49
	v_mul_f32_e32 v51, v17, v49
	v_fma_f32 v52, v14, v48, -v50
	v_fma_f32 v49, v15, v48, v51
	v_mov_b32_e32 v53, v49
	ds_write2_b64 v54, v[46:47], v[52:53] offset1:8
	v_mul_f32_e32 v46, v18, v45
	v_mul_f32_e32 v47, v19, v45
	v_fma_f32 v48, v10, v44, -v46
	v_fma_f32 v45, v11, v44, v47
	v_mov_b32_e32 v49, v45
	v_mul_f32_e32 v44, v20, v43
	v_mul_f32_e32 v45, v21, v43
	v_fma_f32 v46, v12, v42, -v44
	v_fma_f32 v43, v13, v42, v45
	v_mov_b32_e32 v47, v43
	v_sub_f32_e32 v44, v48, v46
	v_sub_f32_e32 v45, v49, v47
	v_add_f32_e32 v42, v48, v46
	v_add_f32_e32 v43, v49, v47
	v_mul_f32_e32 v46, v16, v45
	v_mul_f32_e32 v47, v17, v45
	v_fma_f32 v48, v14, v44, -v46
	v_fma_f32 v45, v15, v44, v47
	v_mov_b32_e32 v49, v45
	ds_write2_b64 v55, v[42:43], v[48:49] offset0:16 offset1:24
	v_mul_f32_e32 v42, v22, v35
	v_mul_f32_e32 v43, v23, v35
	v_fma_f32 v44, v2, v34, -v42
	v_fma_f32 v35, v3, v34, v43
	v_mov_b32_e32 v45, v35
	v_mul_f32_e32 v34, v24, v37
	v_mul_f32_e32 v35, v25, v37
	v_fma_f32 v42, v4, v36, -v34
	v_fma_f32 v35, v5, v36, v35
	v_mov_b32_e32 v43, v35
	v_mul_f32_e32 v34, v26, v39
	v_mul_f32_e32 v35, v27, v39
	v_fma_f32 v36, v6, v38, -v34
	v_fma_f32 v35, v7, v38, v35
	v_mov_b32_e32 v37, v35
	v_mul_f32_e32 v34, v28, v41
	v_mul_f32_e32 v35, v29, v41
	v_fma_f32 v38, v8, v40, -v34
	v_fma_f32 v35, v9, v40, v35
	v_mov_b32_e32 v39, v35
	v_add_f32_e32 v34, v44, v36
	v_add_f32_e32 v35, v45, v37
	v_add_f32_e32 v40, v42, v38
	v_add_f32_e32 v41, v43, v39
	v_sub_f32_e32 v38, v42, v38
	v_sub_f32_e32 v39, v43, v39
	v_add_f32_e32 v42, v34, v40
	v_add_f32_e32 v43, v35, v41
	v_sub_f32_e32 v34, v34, v40
	v_sub_f32_e32 v35, v35, v41
	v_sub_f32_e32 v36, v44, v36
	v_sub_f32_e32 v37, v45, v37
	v_mul_f32_e32 v40, v16, v35
	v_mul_f32_e32 v41, v17, v35
	v_fma_f32 v44, v14, v34, -v40
	v_fma_f32 v35, v15, v34, v41
	v_mov_b32_e32 v45, v35
	v_mul_f32_e32 v34, v18, v37
	v_mul_f32_e32 v35, v19, v37
	ds_write2_b64 v55, v[42:43], v[44:45] offset0:33 offset1:41
	v_fma_f32 v40, v10, v36, -v34
	v_fma_f32 v35, v11, v36, v35
	v_mov_b32_e32 v41, v35
	v_mul_f32_e32 v34, v20, v39
	v_mul_f32_e32 v35, v21, v39
	v_fma_f32 v36, v12, v38, -v34
	v_fma_f32 v35, v13, v38, v35
	v_mov_b32_e32 v37, v35
	v_add_f32_e32 v34, v40, v36
	v_add_f32_e32 v35, v41, v37
	v_sub_f32_e32 v36, v40, v36
	v_sub_f32_e32 v37, v41, v37
	v_mul_f32_e32 v38, v16, v37
	v_mul_f32_e32 v39, v17, v37
	v_fma_f32 v40, v14, v36, -v38
	v_fma_f32 v37, v15, v36, v39
	v_fma_f32 v36, v14, v36, v38
	v_mov_b32_e32 v41, v37
	ds_write2_b64 v55, v[34:35], v[40:41] offset0:50 offset1:58
	s_andn2_b64 exec, exec, s[14:15]
	s_cbranch_execnz .LBB0_678

;     static __device__ __forceinline__ float sl(float g, float up) { return g * __builtin_amdgcn_rcpf(1.0f + __builtin_amdgcn_exp2f(-1.4426950408889634f * g)) * up; }
; #define tid ltid()
; template <int LR, bool INV>
; __device__ __forceinline__ void fft_pass(float2* X, const int N, const int sl, const int tid) {
;     ...
;   for (int g = tid; g < (N >> LR); g += NTHR) {
;     const int r = g & (s - 1);
;     const int i0 = ((g >> sl) << (sl + LR)) + r;
;     float2 x[R];
; #pragma unroll
;     for (int m = 0; m < R; ++m) x[m] = X[PIDX(i0 + (m << sl))];
.LBB0_684:
	v_and_b32_e32 v33, 0xffffffc0, v32
	v_or_b32_e32 v34, v33, v31
	v_ashrrev_i32_e32 v35, 1, v33
	v_or_b32_e32 v36, 16, v33

;     static __device__ __forceinline__ float sl(float g, float up) { return g * __builtin_amdgcn_rcpf(1.0f + __builtin_amdgcn_exp2f(-1.4426950408889634f * g)) * up; }
; #define tid ltid()
; template <int LR, bool INV>
; __device__ __forceinline__ void fft_pass(float2* X, const int N, const int sl, const int tid) {
;     ...
;   for (int g = tid; g < (N >> LR); g += NTHR) {
;     const int r = g & (s - 1);
;     const int i0 = ((g >> sl) << (sl + LR)) + r;
;     float2 x[R];
; #pragma unroll
;     for (int m = 0; m < R; ++m) x[m] = X[PIDX(i0 + (m << sl))];
	v_or_b32_e32 v33, 48, v33
	v_lshl_add_u32 v34, v34, 3, 0
	v_ashrrev_i32_e32 v36, 4, v36

;     static __device__ __forceinline__ float sl(float g, float up) { return g * __builtin_amdgcn_rcpf(1.0f + __builtin_amdgcn_exp2f(-1.4426950408889634f * g)) * up; }
; #define tid ltid()
; template <int LR, bool INV>
; __device__ __forceinline__ void fft_pass(float2* X, const int N, const int sl, const int tid) {
;     ...
;   for (int g = tid; g < (N >> LR); g += NTHR) {
;     const int r = g & (s - 1);
;     const int i0 = ((g >> sl) << (sl + LR)) + r;
;     float2 x[R];
; #pragma unroll
;     for (int m = 0; m < R; ++m) x[m] = X[PIDX(i0 + (m << sl))];
	v_ashrrev_i32_e32 v33, 4, v33
	v_add_u32_e32 v60, v34, v35
	v_lshl_add_u32 v61, v36, 3, v34

;     static __device__ __forceinline__ float sl(float g, float up) { return g * __builtin_amdgcn_rcpf(1.0f + __builtin_amdgcn_exp2f(-1.4426950408889634f * g)) * up; }
; __device__ __forceinline__ float2 cmul(float2 a, float2 b) { return make_float2(a.x * b.x - a.y * b.y, a.x * b.y + a.y * b.x); }
; #define tid ltid()
; template <int LR, bool INV>
; __device__ __forceinline__ void fft_stages(float2 (&x)[1 << LR], const int r, const int s) {
;   constexpr int R = 1 << LR;
; #pragma unroll
;   for (int st = 0; st < LR; ++st) {
;     const int hl = INV ? (1 << st) : (R >> (st + 1));
;     const float fb = (float)r * (0.5f / (float)(hl * s));
;     const float2 wb = make_float2(__builtin_amdgcn_cosf(fb), INV ? __builtin_amdgcn_sinf(fb) : -__builtin_amdgcn_sinf(fb));
; #pragma unroll
;     for (int m = 0; m < R; ++m) {
;       if (m & hl) continue;
;       const int k = m & (hl - 1); const int j = k * (8 / hl);
;       const float2 wc = make_float2(c16(j), INV ? s16(j) : -s16(j));
;       const float2 tw = cmul(wb, wc);
;       if (!INV) { const float2 p = x[m], q = x[m + hl]; x[m] = make_float2(p.x + q.x, p.y + q.y); x[m + hl] = cmul(make_float2(p.x - q.x, p.y - q.y), tw); }
;       else { const float2 p = x[m], q = cmul(x[m + hl], tw); x[m] = make_float2(p.x + q.x, p.y + q.y); x[m + hl] = make_float2(p.x - q.x, p.y - q.y); }
;     }
;   }
; }
; template <int LR, bool INV>
; __device__ __forceinline__ void fft_pass(float2* X, const int N, const int sl, const int tid) {
;   constexpr int R = 1 << LR;
;   const int s = 1 << sl;
;   for (int g = tid; g < (N >> LR); g += NTHR) {
;     const int r = g & (s - 1);
;     const int i0 = ((g >> sl) << (sl + LR)) + r;
;     float2 x[R];
; #pragma unroll
;     for (int m = 0; m < R; ++m) x[m] = X[PIDX(i0 + (m << sl))];
;     fft_stages<LR, INV>(x, r, s);
; #pragma unroll
;     for (int m = 0; m < R; ++m) X[PIDX(i0 + (m << sl))] = x[m];
;   }
	v_lshl_add_u32 v33, v33, 3, v34
	ds_read2_b64 v[34:37], v60 offset1:8
	ds_read2_b64 v[38:41], v61 offset0:16 offset1:24
	ds_read2_b64 v[42:45], v61 offset0:33 offset1:41
	ds_read2_b64 v[46:49], v61 offset0:50 offset1:58
	v_add_u32_e32 v30, 0x200, v30
	s_waitcnt lgkmcnt(3)
	v_mul_f32_e32 v50, v36, v2
	v_mul_f32_e32 v51, v37, v3
	s_waitcnt lgkmcnt(2)
	v_mul_f32_e32 v52, v2, v40
	v_mul_f32_e32 v53, v3, v41
	s_waitcnt lgkmcnt(1)
	v_mul_f32_e32 v54, v2, v44
	v_mul_f32_e32 v55, v3, v45
	s_waitcnt lgkmcnt(0)
	v_mul_f32_e32 v56, v2, v48
	v_mul_f32_e32 v57, v3, v49
	v_fma_f32 v58, v36, v6, -v51
	v_fma_f32 v37, v37, v7, v50
	v_fma_f32 v50, v6, v40, -v53
	v_fma_f32 v41, v7, v41, v52
	v_fma_f32 v52, v6, v44, -v55
	v_fma_f32 v45, v7, v45, v54
	v_fma_f32 v54, v6, v48, -v57
	v_fma_f32 v49, v7, v49, v56
	v_mov_b32_e32 v51, v41
	v_mov_b32_e32 v55, v49
	v_mov_b32_e32 v53, v45
	v_sub_f32_e32 v40, v38, v50
	v_sub_f32_e32 v41, v39, v51
	v_add_f32_e32 v48, v46, v54
	v_add_f32_e32 v49, v47, v55
	v_add_f32_e32 v38, v38, v50
	v_add_f32_e32 v39, v39, v51
	v_sub_f32_e32 v46, v46, v54
	v_sub_f32_e32 v47, v47, v55
	v_mov_b32_e32 v59, v37
	v_add_f32_e32 v44, v42, v52
	v_add_f32_e32 v45, v43, v53
	v_sub_f32_e32 v42, v42, v52
	v_sub_f32_e32 v43, v43, v53
	v_mul_f32_e32 v50, v4, v40
	v_mul_f32_e32 v51, v5, v41
	v_mul_f32_e32 v52, v10, v48
	v_mul_f32_e32 v53, v11, v49
	v_mul_f32_e32 v54, v10, v38
	v_mul_f32_e32 v55, v11, v39
	v_mul_f32_e32 v56, v4, v46
	v_mul_f32_e32 v57, v5, v47
	v_sub_f32_e32 v36, v34, v58
	v_sub_f32_e32 v37, v35, v59
	v_add_f32_e32 v34, v34, v58
	v_add_f32_e32 v35, v35, v59
	v_fma_f32 v58, v12, v40, -v51
	v_fma_f32 v41, v13, v41, v50
	v_fma_f32 v50, v8, v48, -v53
	v_fma_f32 v49, v9, v49, v52
	v_fma_f32 v52, v8, v38, -v55
	v_fma_f32 v39, v9, v39, v54
	v_fma_f32 v54, v12, v46, -v57
	v_fma_f32 v47, v13, v47, v56
	v_mov_b32_e32 v51, v49
	v_mov_b32_e32 v55, v47
	v_mov_b32_e32 v59, v41
	v_mov_b32_e32 v53, v39
	v_sub_f32_e32 v40, v44, v50
	v_sub_f32_e32 v41, v45, v51
	v_add_f32_e32 v44, v44, v50
	v_add_f32_e32 v45, v45, v51
	v_add_f32_e32 v48, v42, v54
	v_add_f32_e32 v49, v43, v55
	v_sub_f32_e32 v46, v34, v52
	v_sub_f32_e32 v47, v35, v53
	v_add_f32_e32 v34, v34, v52
	v_add_f32_e32 v35, v35, v53
	v_sub_f32_e32 v42, v42, v54
	v_sub_f32_e32 v43, v43, v55
	v_mul_f32_e32 v50, v20, v41
	v_mul_f32_e32 v51, v21, v40
	v_mul_f32_e32 v52, v16, v45
	v_mul_f32_e32 v53, v17, v44
	v_mul_f32_e32 v54, v22, v49
	v_mul_f32_e32 v55, v23, v48
	v_sub_f32_e32 v38, v36, v58
	v_sub_f32_e32 v39, v37, v59
	v_add_f32_e32 v36, v36, v58
	v_add_f32_e32 v37, v37, v59
	v_mul_f32_e32 v56, v28, v43
	v_mul_f32_e32 v57, v29, v43
	v_fma_f32 v58, v18, v40, -v50
	v_fma_f32 v41, v19, v41, v51
	v_fma_f32 v50, v14, v44, -v52
	v_fma_f32 v45, v15, v45, v53
	v_fma_f32 v52, v26, v48, -v54
	v_fma_f32 v49, v27, v49, v55
	v_cmp_le_i32_e32 vcc, s21, v30
	v_fma_f32 v54, v24, v42, -v56
	v_fma_f32 v43, v25, v42, v57
	v_mov_b32_e32 v51, v45
	v_mov_b32_e32 v53, v49
	v_add_u32_e32 v32, 0x1000, v32
	s_or_b64 s[14:15], vcc, s[14:15]
	v_mov_b32_e32 v59, v41
	v_mov_b32_e32 v55, v43
	v_add_f32_e32 v42, v34, v50
	v_add_f32_e32 v43, v35, v51
	v_add_f32_e32 v44, v36, v52
	v_add_f32_e32 v45, v37, v53
	v_add_f32_e32 v40, v46, v58
	v_add_f32_e32 v41, v47, v59
	v_add_f32_e32 v48, v38, v54
	v_add_f32_e32 v49, v39, v55
	v_sub_f32_e32 v34, v34, v50
	v_sub_f32_e32 v35, v35, v51
	v_sub_f32_e32 v36, v36, v52
	v_sub_f32_e32 v37, v37, v53
	v_sub_f32_e32 v46, v46, v58
	v_sub_f32_e32 v47, v47, v59
	v_sub_f32_e32 v38, v38, v54
	v_sub_f32_e32 v39, v39, v55
	ds_write2_b64 v60, v[42:43], v[44:45] offset1:8
	ds_write2_b64 v61, v[40:41], v[48:49] offset0:16 offset1:24
	ds_write2_b64 v61, v[34:35], v[36:37] offset0:33 offset1:41
	ds_write2_b64 v61, v[46:47], v[38:39] offset0:50 offset1:58
	s_andn2_b64 exec, exec, s[14:15]
	s_cbranch_execnz .LBB0_684

;     static __device__ __forceinline__ float sl(float g, float up) { return g * __builtin_amdgcn_rcpf(1.0f + __builtin_amdgcn_exp2f(-1.4426950408889634f * g)) * up; }
; #define tid ltid()
; template <int LR, bool INV>
; __device__ __forceinline__ void fft_pass(float2* X, const int N, const int sl, const int tid) {
;     ...
;   for (int g = tid; g < (N >> LR); g += NTHR) {
;     const int r = g & (s - 1);
;     const int i0 = ((g >> sl) << (sl + LR)) + r;
;     float2 x[R];
; #pragma unroll
;     for (int m = 0; m < R; ++m) x[m] = X[PIDX(i0 + (m << sl))];
.LBB0_687:
	v_and_or_b32 v33, v32, s53, v31
	v_ashrrev_i32_e32 v34, 4, v33
	v_lshl_add_u32 v35, v33, 3, 0
	v_or_b32_e32 v36, 64, v33


;     static __device__ __forceinline__ float sl(float g, float up) { return g * __builtin_amdgcn_rcpf(1.0f + __builtin_amdgcn_exp2f(-1.4426950408889634f * g)) * up; }
; #define tid ltid()
; template <int LR, bool INV>
; __device__ __forceinline__ void fft_pass(float2* X, const int N, const int sl, const int tid) {
;     ...
;   for (int g = tid; g < (N >> LR); g += NTHR) {
;     const int r = g & (s - 1);
;     const int i0 = ((g >> sl) << (sl + LR)) + r;
;     float2 x[R];
; #pragma unroll
;     for (int m = 0; m < R; ++m) x[m] = X[PIDX(i0 + (m << sl))];
	v_or_b32_e32 v33, 0x1c0, v33
	v_lshl_add_u32 v60, v34, 3, v35
	v_ashrrev_i32_e32 v34, 4, v36


;     static __device__ __forceinline__ float sl(float g, float up) { return g * __builtin_amdgcn_rcpf(1.0f + __builtin_amdgcn_exp2f(-1.4426950408889634f * g)) * up; }
; #define tid ltid()
; template <int LR, bool INV>
; __device__ __forceinline__ void fft_pass(float2* X, const int N, const int sl, const int tid) {
;     ...
;   for (int g = tid; g < (N >> LR); g += NTHR) {
;     const int r = g & (s - 1);
;     const int i0 = ((g >> sl) << (sl + LR)) + r;
;     float2 x[R];
; #pragma unroll
;     for (int m = 0; m < R; ++m) x[m] = X[PIDX(i0 + (m << sl))];
	v_ashrrev_i32_e32 v33, 4, v33
	v_lshl_add_u32 v61, v34, 3, v35


;     static __device__ __forceinline__ float sl(float g, float up) { return g * __builtin_amdgcn_rcpf(1.0f + __builtin_amdgcn_exp2f(-1.4426950408889634f * g)) * up; }
; __device__ __forceinline__ float2 cmul(float2 a, float2 b) { return make_float2(a.x * b.x - a.y * b.y, a.x * b.y + a.y * b.x); }
; #define tid ltid()
; template <int LR, bool INV>
; __device__ __forceinline__ void fft_stages(float2 (&x)[1 << LR], const int r, const int s) {
;   constexpr int R = 1 << LR;
; #pragma unroll
;   for (int st = 0; st < LR; ++st) {
;     const int hl = INV ? (1 << st) : (R >> (st + 1));
;     const float fb = (float)r * (0.5f / (float)(hl * s));
;     const float2 wb = make_float2(__builtin_amdgcn_cosf(fb), INV ? __builtin_amdgcn_sinf(fb) : -__builtin_amdgcn_sinf(fb));
; #pragma unroll
;     for (int m = 0; m < R; ++m) {
;       if (m & hl) continue;
;       const int k = m & (hl - 1); const int j = k * (8 / hl);
;       const float2 wc = make_float2(c16(j), INV ? s16(j) : -s16(j));
;       const float2 tw = cmul(wb, wc);
;       if (!INV) { const float2 p = x[m], q = x[m + hl]; x[m] = make_float2(p.x + q.x, p.y + q.y); x[m + hl] = cmul(make_float2(p.x - q.x, p.y - q.y), tw); }
;       else { const float2 p = x[m], q = cmul(x[m + hl], tw); x[m] = make_float2(p.x + q.x, p.y + q.y); x[m + hl] = make_float2(p.x - q.x, p.y - q.y); }
;     }
;   }
; }
; template <int LR, bool INV>
; __device__ __forceinline__ void fft_pass(float2* X, const int N, const int sl, const int tid) {
;   constexpr int R = 1 << LR;
;   const int s = 1 << sl;
;   for (int g = tid; g < (N >> LR); g += NTHR) {
;     const int r = g & (s - 1);
;     const int i0 = ((g >> sl) << (sl + LR)) + r;
;     float2 x[R];
; #pragma unroll
;     for (int m = 0; m < R; ++m) x[m] = X[PIDX(i0 + (m << sl))];
;     fft_stages<LR, INV>(x, r, s);
; #pragma unroll
;     for (int m = 0; m < R; ++m) X[PIDX(i0 + (m << sl))] = x[m];
;   }
	v_lshl_add_u32 v33, v33, 3, v35
	ds_read_b64 v[34:35], v60
	ds_read_b64 v[36:37], v60 offset:544
	ds_read_b64 v[38:39], v60 offset:1088
	ds_read_b64 v[40:41], v60 offset:1632
	ds_read_b64 v[42:43], v60 offset:2176
	ds_read_b64 v[44:45], v60 offset:2720
	ds_read_b64 v[46:47], v60 offset:3808
	ds_read_b64 v[48:49], v60 offset:3264
	s_waitcnt lgkmcnt(6)
	v_mul_f32_e32 v50, v36, v2
	v_mul_f32_e32 v51, v37, v3
	s_waitcnt lgkmcnt(4)
	v_mul_f32_e32 v52, v2, v40
	v_mul_f32_e32 v53, v3, v41
	s_waitcnt lgkmcnt(2)
	v_mul_f32_e32 v54, v2, v44
	v_mul_f32_e32 v55, v3, v45
	s_waitcnt lgkmcnt(1)
	v_mul_f32_e32 v56, v2, v46
	v_mul_f32_e32 v57, v3, v47
	v_fma_f32 v58, v36, v6, -v51
	v_fma_f32 v37, v37, v7, v50
	v_fma_f32 v50, v6, v40, -v53
	v_fma_f32 v41, v7, v41, v52
	v_fma_f32 v52, v6, v44, -v55
	v_fma_f32 v45, v7, v45, v54
	v_fma_f32 v54, v6, v46, -v57
	v_fma_f32 v47, v7, v47, v56
	v_mov_b32_e32 v51, v41
	v_mov_b32_e32 v55, v47
	v_mov_b32_e32 v53, v45
	v_sub_f32_e32 v40, v38, v50
	v_sub_f32_e32 v41, v39, v51
	s_waitcnt lgkmcnt(0)
	v_add_f32_e32 v46, v48, v54
	v_add_f32_e32 v47, v49, v55
	v_mov_b32_e32 v59, v37
	v_add_f32_e32 v44, v42, v52
	v_add_f32_e32 v45, v43, v53
	v_add_f32_e32 v38, v38, v50
	v_add_f32_e32 v39, v39, v51
	v_sub_f32_e32 v42, v42, v52
	v_sub_f32_e32 v43, v43, v53
	v_sub_f32_e32 v48, v48, v54
	v_sub_f32_e32 v49, v49, v55
	v_mul_f32_e32 v50, v4, v40
	v_mul_f32_e32 v51, v5, v41
	v_mul_f32_e32 v52, v10, v46
	v_mul_f32_e32 v53, v11, v47
	v_sub_f32_e32 v36, v34, v58
	v_sub_f32_e32 v37, v35, v59
	v_add_f32_e32 v34, v34, v58
	v_add_f32_e32 v35, v35, v59
	v_mul_f32_e32 v54, v10, v38
	v_mul_f32_e32 v55, v11, v39
	v_mul_f32_e32 v56, v4, v48
	v_mul_f32_e32 v57, v5, v49
	v_fma_f32 v58, v12, v40, -v51
	v_fma_f32 v41, v13, v41, v50
	v_fma_f32 v50, v8, v46, -v53
	v_fma_f32 v47, v9, v47, v52
	v_fma_f32 v52, v8, v38, -v55
	v_fma_f32 v39, v9, v39, v54
	v_fma_f32 v54, v12, v48, -v57
	v_fma_f32 v49, v13, v49, v56
	v_mov_b32_e32 v51, v47
	v_mov_b32_e32 v59, v41
	v_mov_b32_e32 v53, v39
	v_mov_b32_e32 v55, v49
	v_sub_f32_e32 v40, v44, v50
	v_sub_f32_e32 v41, v45, v51
	v_add_f32_e32 v44, v44, v50
	v_add_f32_e32 v45, v45, v51
	v_sub_f32_e32 v46, v34, v52
	v_sub_f32_e32 v47, v35, v53
	v_add_f32_e32 v34, v34, v52
	v_add_f32_e32 v35, v35, v53
	v_add_f32_e32 v48, v42, v54
	v_add_f32_e32 v49, v43, v55
	v_sub_f32_e32 v42, v42, v54
	v_sub_f32_e32 v43, v43, v55
	v_mul_f32_e32 v50, v20, v41
	v_mul_f32_e32 v51, v21, v40
	v_mul_f32_e32 v52, v16, v45
	v_mul_f32_e32 v53, v17, v44
	v_add_u32_e32 v30, 0x200, v30
	v_sub_f32_e32 v38, v36, v58
	v_sub_f32_e32 v39, v37, v59
	v_add_f32_e32 v36, v36, v58
	v_add_f32_e32 v37, v37, v59
	v_mul_f32_e32 v54, v22, v49
	v_mul_f32_e32 v55, v23, v48
	v_mul_f32_e32 v56, v28, v43
	v_mul_f32_e32 v57, v29, v43
	v_fma_f32 v58, v18, v40, -v50
	v_fma_f32 v41, v19, v41, v51
	v_fma_f32 v50, v14, v44, -v52
	v_fma_f32 v45, v15, v45, v53
	v_cmp_le_i32_e32 vcc, s21, v30
	v_fma_f32 v52, v26, v48, -v54
	v_fma_f32 v49, v27, v49, v55
	v_fma_f32 v54, v24, v42, -v56
	v_fma_f32 v43, v25, v42, v57
	v_mov_b32_e32 v51, v45
	v_add_u32_e32 v32, 0x1000, v32
	s_or_b64 s[14:15], vcc, s[14:15]
	v_mov_b32_e32 v59, v41
	v_mov_b32_e32 v53, v49
	v_mov_b32_e32 v55, v43
	v_add_f32_e32 v42, v34, v50
	v_add_f32_e32 v43, v35, v51
	v_add_f32_e32 v40, v46, v58
	v_add_f32_e32 v41, v47, v59
	v_add_f32_e32 v44, v36, v52
	v_add_f32_e32 v45, v37, v53
	v_add_f32_e32 v48, v38, v54
	v_add_f32_e32 v49, v39, v55
	v_sub_f32_e32 v34, v34, v50
	v_sub_f32_e32 v35, v35, v51
	v_sub_f32_e32 v36, v36, v52
	v_sub_f32_e32 v37, v37, v53
	v_sub_f32_e32 v46, v46, v58
	v_sub_f32_e32 v47, v47, v59
	v_sub_f32_e32 v38, v38, v54
	v_sub_f32_e32 v39, v39, v55
	ds_write_b64 v60, v[42:43]
	ds_write_b64 v60, v[44:45] offset:544
	ds_write_b64 v60, v[40:41] offset:1088
	ds_write_b64 v60, v[48:49] offset:1632
	ds_write_b64 v60, v[34:35] offset:2176
	ds_write_b64 v60, v[36:37] offset:2720
	ds_write_b64 v60, v[46:47] offset:3264
	ds_write_b64 v60, v[38:39] offset:3808
	s_andn2_b64 exec, exec, s[14:15]
	s_cbranch_execnz .LBB0_687
